# phase-0 weight conversion: register 4x4 transpose, two tiles in flight, no LDS round trip / barriers / per-stage gain loads
# baseline (speedup 1.0000x reference)
; #define LAS __attribute__((address_space(3)))
; __device__ __forceinline__ int opq_tid() { int t = threadIdx.x; asm volatile("" : "+v"(t)); return t; }
; __device__ __forceinline__ int opq_bid() { int b = blockIdx.x; asm volatile("" : "+s"(b)); return b; }
; __device__ __forceinline__ void convert_weight_v4(LAS unsigned char* lds, const float* W, bf16_t* Bt, int K, int Nsrc, int Ndst, const float* gain, int mode) {
;     LAS float* tile = (LAS float*)lds;
;     const int tid = opq_tid(), nkt = K / 64, nnt = Ndst / 256;
;     for (int t = opq_bid(); t < nkt * nnt; t += gridDim.x) {
;         const int k0 = (t % nkt) * 64, pn = t / nkt, n0 = pn * 256;
;         f32x4 v[8];
; #pragma unroll
;         for (int i = 0; i < 8; ++i) {
;             const int e = tid + i * 512, kk = e >> 6, n4 = e & 63;
;             const int n = (mode == 1) ? (n4 >> 5) * FF + pn * 128 + (n4 & 31) * 4 : n0 + n4 * 4;
;             v[i] = (f32x4){0.f, 0.f, 0.f, 0.f};
;             if (n < Nsrc) v[i] = ld_nt(W + (size_t)(k0 + kk) * Nsrc + n);
;         }
; __device__ __forceinline__ void prologue(LAS unsigned char* lds, const Params& P) {
;     ...
;     for (int l = 0; l < 2; ++l) {
;         convert_weight_v4(lds, in[10] + (size_t)l * D * 2 * FF, (bf16_t*)(ws + W_GU + (size_t)(l * 2 + 0) * W_GU_SZ), D, 2 * FF, 2 * FF, in[9] + l * D, 1);
;         convert_weight_v4(lds, in[14] + (size_t)l * D * 2 * FF, (bf16_t*)(ws + W_GU + (size_t)(l * 2 + 1) * W_GU_SZ), D, 2 * FF, 2 * FF, in[13] + l * D, 1);
;         convert_weight_v4(lds, in[11] + (size_t)l * FF * D, (bf16_t*)(ws + W_DN + (size_t)(l * 2 + 0) * W_DN_SZ), FF, D, D, nullptr, 0);
;         convert_weight_v4(lds, in[15] + (size_t)l * FF * D, (bf16_t*)(ws + W_DN + (size_t)(l * 2 + 1) * W_DN_SZ), FF, D, D, nullptr, 0);
;     }
;     convert_weight_v4(lds, in[16], (bf16_t*)(ws + W_IN0), D, 3072, 3072, in[12], 0);
;     convert_weight_v4(lds, in[23], (bf16_t*)(ws + W_OUT0), D, D, D, nullptr, 0);
;     convert_weight_v4(lds, in[24], (bf16_t*)(ws + W_IN1), D, 672, 768, in[12] + D, 0);
;     convert_weight(lds, in[27], (bf16_t*)(ws + W_QUP), 384, 1536, 1536, in[25], 2);
;     convert_weight_v4(lds, in[28], (bf16_t*)(ws + W_KVUP), 256, 2048, 2048, nullptr, 0);
;     convert_weight_v4(lds, in[29], (bf16_t*)(ws + W_OUT1), D, D, D, nullptr, 0);
.LBB0_17:
	s_load_dwordx16 s[36:51], s[0:1], 0x0
	v_writelane_b32 v255, s12, 3
	s_add_u32 s92, s88, 0x956a000
	s_addc_u32 s93, s89, 0
	s_cmp_lt_i32 s90, 1
	s_waitcnt lgkmcnt(0)
	v_writelane_b32 v255, s36, 4
	s_mov_b32 s5, 0
	s_nop 0
	v_writelane_b32 v255, s37, 5
	v_writelane_b32 v255, s38, 6
	v_writelane_b32 v255, s39, 7
	v_writelane_b32 v255, s40, 8
	v_writelane_b32 v255, s41, 9
	v_writelane_b32 v255, s42, 10
	v_writelane_b32 v255, s43, 11
	v_writelane_b32 v255, s44, 12
	v_writelane_b32 v255, s45, 13
	v_writelane_b32 v255, s46, 14
	v_writelane_b32 v255, s47, 15
	v_writelane_b32 v255, s48, 16
	v_writelane_b32 v255, s49, 17
	v_writelane_b32 v255, s50, 18
	v_writelane_b32 v255, s51, 19
	s_load_dwordx16 s[56:71], s[0:1], 0x40
	s_load_dwordx16 s[72:87], s[0:1], 0x80
	s_load_dwordx16 s[40:55], s[0:1], 0xc0
	s_cselect_b64 s[0:1], -1, 0
	s_cmp_gt_i32 s91, 0
	s_cselect_b64 s[2:3], -1, 0
	s_waitcnt lgkmcnt(0)
	v_writelane_b32 v255, s72, 20
	s_and_b64 s[2:3], s[0:1], s[2:3]
	s_andn2_b64 vcc, exec, s[2:3]
	v_writelane_b32 v255, s73, 21
	v_writelane_b32 v255, s74, 22
	v_writelane_b32 v255, s75, 23
	v_writelane_b32 v255, s76, 24
	v_writelane_b32 v255, s77, 25
	v_writelane_b32 v255, s78, 26
	v_writelane_b32 v255, s79, 27
	v_writelane_b32 v255, s80, 28
	v_writelane_b32 v255, s81, 29
	v_writelane_b32 v255, s82, 30
	v_writelane_b32 v255, s83, 31
	v_writelane_b32 v255, s84, 32
	v_writelane_b32 v255, s85, 33
	v_writelane_b32 v255, s86, 34
	v_writelane_b32 v255, s87, 35
	s_cbranch_vccnz .LBB0_301
	v_and_b32_e32 v0, 63, v254
	v_lshrrev_b32_e32 v1, 6, v254
	v_and_b32_e32 v120, 7, v0
	v_bfe_u32 v121, v0, 3, 3
	v_add_u32_e32 v122, 0, v1
	v_and_b32_e32 v123, 1, v122
	v_lshl_add_u32 v123, v123, 3, v120
	v_lshlrev_b32_e32 v2, 2, v123
	v_lshrrev_b32_e32 v122, 1, v122
	v_lshl_add_u32 v122, v122, 3, v121
	v_lshlrev_b32_e32 v4, 2, v122
	v_lshlrev_b32_e32 v8, 2, v4
	v_add_u32_e32 v122, 0xa80, v4
	v_cmp_gt_u32_e32 vcc, 0x80, v4
	s_nop 1
	v_cndmask_b32_e32 v122, v122, v4, vcc
	v_lshlrev_b32_e32 v6, 2, v122
	v_lshlrev_b32_e32 v10, 2, v2
	v_lshlrev_b32_e32 v12, 1, v2
	v_add_u32_e32 v122, 8, v1
	v_and_b32_e32 v123, 1, v122
	v_lshl_add_u32 v123, v123, 3, v120
	v_lshlrev_b32_e32 v3, 2, v123
	v_lshrrev_b32_e32 v122, 1, v122
	v_lshl_add_u32 v122, v122, 3, v121
	v_lshlrev_b32_e32 v5, 2, v122
	v_lshlrev_b32_e32 v9, 2, v5
	v_add_u32_e32 v122, 0xa80, v5
	v_cmp_gt_u32_e32 vcc, 0x80, v5
	s_nop 1
	v_cndmask_b32_e32 v122, v122, v5, vcc
	v_lshlrev_b32_e32 v7, 2, v122
	v_lshlrev_b32_e32 v11, 2, v3
	v_lshlrev_b32_e32 v13, 1, v3
	s_mov_b32 s35, s18
	s_cmpk_lt_u32 s35, 0x9d0
	s_cbranch_scc0 .Lwc_done
	s_cmpk_lt_u32 s35, 0x580
	s_cbranch_scc0 .Lwc_p1_a0
	s_mov_b32 s21, 0
	s_mov_b32 s22, s35
	s_cmpk_lt_u32 s22, 0x160
	s_cbranch_scc1 .Lwc_gu_a0
	s_sub_u32 s22, s22, 0x160
	s_add_u32 s21, s21, 1
	s_cmpk_lt_u32 s22, 0x160
	s_cbranch_scc1 .Lwc_gu_a0
	s_sub_u32 s22, s22, 0x160
	s_add_u32 s21, s21, 1
	s_cmpk_lt_u32 s22, 0x160
	s_cbranch_scc1 .Lwc_gu_a0
	s_sub_u32 s22, s22, 0x160
	s_add_u32 s21, s21, 1
.Lwc_gu_a0:
	s_lshr_b32 s23, s22, 4
	s_and_b32 s22, s22, 15
	s_and_b32 s30, s21, 1
	s_lshr_b32 s31, s21, 1
	s_cmp_eq_u32 s30, 0
	s_cselect_b32 s24, s60, s68
	s_cselect_b32 s25, s61, s69
	s_cselect_b32 s28, s58, s66
	s_cselect_b32 s29, s59, s67
	s_mul_i32 s30, s31, 0x1600000
	s_add_u32 s24, s24, s30
	s_addc_u32 s25, s25, 0
	s_lshl_b32 s30, s31, 12
	s_add_u32 s28, s28, s30
	s_addc_u32 s29, s29, 0
	s_mul_i32 s30, s21, 0xb00000
	s_add_u32 s26, s88, s30
	s_addc_u32 s27, s89, 0
	s_mul_i32 s30, s22, 0x160000
	s_mul_i32 s31, s23, 0x200
	s_add_u32 s30, s30, s31
	s_add_u32 s2, s24, s30
	s_addc_u32 s3, s25, 0
	s_mul_i32 s30, s23, 0x80000
	s_lshl_b32 s31, s22, 7
	s_add_u32 s30, s30, s31
	s_add_u32 s6, s26, s30
	s_addc_u32 s7, s27, 0
	s_lshl_b32 s30, s22, 8
	s_add_u32 s8, s28, s30
	s_addc_u32 s9, s29, 0
	s_mov_b32 s15, 1
	s_mov_b32 s10, 0x5800
	s_mov_b32 s11, 0x800
	s_mov_b64 s[12:13], -1
	s_mov_b32 s14, 0x7fffffff
	s_branch .Lwc_pdone_a0
.Lwc_p1_a0:
	s_cmpk_lt_u32 s35, 0x840
	s_cbranch_scc0 .Lwc_p2_a0
	s_mov_b32 s21, 0
	s_sub_u32 s22, s35, 0x580
	s_cmpk_lt_u32 s22, 0xb0
	s_cbranch_scc1 .Lwc_dn_a0
	s_sub_u32 s22, s22, 0xb0
	s_add_u32 s21, s21, 1
	s_cmpk_lt_u32 s22, 0xb0
	s_cbranch_scc1 .Lwc_dn_a0
	s_sub_u32 s22, s22, 0xb0
	s_add_u32 s21, s21, 1
	s_cmpk_lt_u32 s22, 0xb0
	s_cbranch_scc1 .Lwc_dn_a0
	s_sub_u32 s22, s22, 0xb0
	s_add_u32 s21, s21, 1
.Lwc_dn_a0:
	s_and_b32 s23, s22, 3
	s_lshr_b32 s22, s22, 2
	s_and_b32 s30, s21, 1
	s_lshr_b32 s31, s21, 1
	s_cmp_eq_u32 s30, 0
	s_cselect_b32 s24, s62, s70
	s_cselect_b32 s25, s63, s71
	s_mul_i32 s30, s31, 0xb00000
	s_add_u32 s24, s24, s30
	s_addc_u32 s25, s25, 0
	s_mul_i32 s30, s21, 0x580000
	s_add_u32 s30, s30, 0x2c00000
	s_add_u32 s26, s88, s30
	s_addc_u32 s27, s89, 0
	s_mul_i32 s30, s22, 0x40000
	s_mul_i32 s31, s23, 0x400
	s_add_u32 s30, s30, s31
	s_add_u32 s2, s24, s30
	s_addc_u32 s3, s25, 0
	s_mul_i32 s30, s23, 0x160000
	s_lshl_b32 s31, s22, 7
	s_add_u32 s30, s30, s31
	s_add_u32 s6, s26, s30
	s_addc_u32 s7, s27, 0
	s_mov_b64 s[8:9], s[2:3]
	s_mov_b32 s15, 0
	s_mov_b32 s10, 0x1000
	s_mov_b32 s11, 0x1600
	s_mov_b64 s[12:13], 0
	s_mov_b32 s14, 0x7fffffff
	s_branch .Lwc_pdone_a0
; __device__ __forceinline__ f32x4 ld_nt(const float* p) { return __builtin_nontemporal_load((const f32x4*)p); }
; __device__ __forceinline__ void convert_weight_v4(LAS unsigned char* lds, const float* W, bf16_t* Bt, int K, int Nsrc, int Ndst, const float* gain, int mode) {
;     ...
;         const int k0 = (t % nkt) * 64, pn = t / nkt, n0 = pn * 256;
;         f32x4 v[8];
; #pragma unroll
;         for (int i = 0; i < 8; ++i) {
;             const int e = tid + i * 512, kk = e >> 6, n4 = e & 63;
;             const int n = (mode == 1) ? (n4 >> 5) * FF + pn * 128 + (n4 & 31) * 4 : n0 + n4 * 4;
;             v[i] = (f32x4){0.f, 0.f, 0.f, 0.f};
;             if (n < Nsrc) v[i] = ld_nt(W + (size_t)(k0 + kk) * Nsrc + n);
; __device__ __forceinline__ void prologue(LAS unsigned char* lds, const Params& P) {
;     ...
;     convert_weight_v4(lds, in[16], (bf16_t*)(ws + W_IN0), D, 3072, 3072, in[12], 0);
;     convert_weight_v4(lds, in[23], (bf16_t*)(ws + W_OUT0), D, D, D, nullptr, 0);
;     convert_weight_v4(lds, in[24], (bf16_t*)(ws + W_IN1), D, 672, 768, in[12] + D, 0);
;     convert_weight(lds, in[27], (bf16_t*)(ws + W_QUP), 384, 1536, 1536, in[25], 2);
;     convert_weight_v4(lds, in[28], (bf16_t*)(ws + W_KVUP), 256, 2048, 2048, nullptr, 0);
;     convert_weight_v4(lds, in[29], (bf16_t*)(ws + W_OUT1), D, D, D, nullptr, 0);
.Lwc_p2_a0:
	s_cmpk_lt_u32 s35, 0x900
	s_cbranch_scc0 .Lwc_p3_a0
	s_sub_u32 s22, s35, 0x840
	s_lshr_b32 s23, s22, 4
	s_and_b32 s22, s22, 15
	s_mov_b64 s[24:25], s[72:73]
	s_mov_b64 s[28:29], s[64:65]
	s_add_u32 s26, s88, 0x4200000
	s_addc_u32 s27, s89, 0
	s_mul_i32 s30, s22, 0xc0000
	s_mul_i32 s31, s23, 0x400
	s_add_u32 s30, s30, s31
	s_add_u32 s2, s24, s30
	s_addc_u32 s3, s25, 0
	s_mul_i32 s30, s23, 0x80000
	s_lshl_b32 s31, s22, 7
	s_add_u32 s30, s30, s31
	s_add_u32 s6, s26, s30
	s_addc_u32 s7, s27, 0
	s_lshl_b32 s30, s22, 8
	s_add_u32 s8, s28, s30
	s_addc_u32 s9, s29, 0
	s_mov_b32 s15, 1
	s_mov_b32 s10, 0x3000
	s_mov_b32 s11, 0x800
	s_mov_b64 s[12:13], 0
	s_mov_b32 s14, 0x7fffffff
	s_branch .Lwc_pdone_a0
.Lwc_p3_a0:
	s_cmpk_lt_u32 s35, 0x940
	s_cbranch_scc0 .Lwc_p4_a0
	s_sub_u32 s22, s35, 0x900
	s_lshr_b32 s23, s22, 4
	s_and_b32 s22, s22, 15
	s_mov_b64 s[24:25], s[86:87]
	s_add_u32 s26, s88, 0x4800000
	s_addc_u32 s27, s89, 0
	s_mul_i32 s30, s22, 0x40000
	s_mul_i32 s31, s23, 0x400
	s_add_u32 s30, s30, s31
	s_add_u32 s2, s24, s30
	s_addc_u32 s3, s25, 0
	s_mul_i32 s30, s23, 0x80000
	s_lshl_b32 s31, s22, 7
	s_add_u32 s30, s30, s31
	s_add_u32 s6, s26, s30
	s_addc_u32 s7, s27, 0
	s_mov_b64 s[8:9], s[2:3]
	s_mov_b32 s15, 0
	s_mov_b32 s10, 0x1000
	s_mov_b32 s11, 0x800
	s_mov_b64 s[12:13], 0
	s_mov_b32 s14, 0x7fffffff
	s_branch .Lwc_pdone_a0
.Lwc_p4_a0:
	s_cmpk_lt_u32 s35, 0x970
	s_cbranch_scc0 .Lwc_p5_a0
	s_sub_u32 s22, s35, 0x940
	s_lshr_b32 s23, s22, 4
	s_and_b32 s22, s22, 15
	s_mov_b64 s[24:25], s[40:41]
	s_add_u32 s28, s64, 0x1000
	s_addc_u32 s29, s65, 0
	s_add_u32 s26, s88, 0x4a00000
	s_addc_u32 s27, s89, 0
	s_mul_i32 s30, s22, 0x2a000
	s_mul_i32 s31, s23, 0x400
	s_add_u32 s30, s30, s31
	s_add_u32 s2, s24, s30
	s_addc_u32 s3, s25, 0
	s_mul_i32 s30, s23, 0x80000
	s_lshl_b32 s31, s22, 7
	s_add_u32 s30, s30, s31
	s_add_u32 s6, s26, s30
	s_addc_u32 s7, s27, 0
	s_lshl_b32 s30, s22, 8
	s_add_u32 s8, s28, s30
	s_addc_u32 s9, s29, 0
	s_mov_b32 s15, 1
	s_mov_b32 s10, 0xa80
	s_mov_b32 s11, 0x800
	s_mov_b64 s[12:13], 0
	s_lshl_b32 s30, s23, 8
	s_sub_u32 s14, 0x2a0, s30
	s_branch .Lwc_pdone_a0
.Lwc_p5_a0:
	s_cmpk_lt_u32 s35, 0x990
	s_cbranch_scc0 .Lwc_p6_a0
	s_sub_u32 s22, s35, 0x970
	s_lshr_b32 s23, s22, 2
	s_and_b32 s22, s22, 3
	s_mov_b64 s[24:25], s[48:49]
	s_add_u32 s26, s88, 0x4ca0000
	s_addc_u32 s27, s89, 0
	s_mul_i32 s30, s22, 0x80000
	s_mul_i32 s31, s23, 0x400
	s_add_u32 s30, s30, s31
	s_add_u32 s2, s24, s30
	s_addc_u32 s3, s25, 0
	s_mul_i32 s30, s23, 0x20000
	s_lshl_b32 s31, s22, 7
	s_add_u32 s30, s30, s31
	s_add_u32 s6, s26, s30
	s_addc_u32 s7, s27, 0
	s_mov_b64 s[8:9], s[2:3]
	s_mov_b32 s15, 0
	s_mov_b32 s10, 0x2000
	s_mov_b32 s11, 0x200
	s_mov_b64 s[12:13], 0
	s_mov_b32 s14, 0x7fffffff
	s_branch .Lwc_pdone_a0
.Lwc_p6_a0:
	s_sub_u32 s22, s35, 0x990
	s_lshr_b32 s23, s22, 4
	s_and_b32 s22, s22, 15
	s_mov_b64 s[24:25], s[50:51]
	s_add_u32 s26, s88, 0x4da0000
	s_addc_u32 s27, s89, 0
	s_mul_i32 s30, s22, 0x40000
	s_mul_i32 s31, s23, 0x400
	s_add_u32 s30, s30, s31
	s_add_u32 s2, s24, s30
	s_addc_u32 s3, s25, 0
	s_mul_i32 s30, s23, 0x80000
	s_lshl_b32 s31, s22, 7
	s_add_u32 s30, s30, s31
	s_add_u32 s6, s26, s30
	s_addc_u32 s7, s27, 0
	s_mov_b64 s[8:9], s[2:3]
	s_mov_b32 s15, 0
	s_mov_b32 s10, 0x1000
	s_mov_b32 s11, 0x800
	s_mov_b64 s[12:13], 0
	s_mov_b32 s14, 0x7fffffff
	s_branch .Lwc_pdone_a0
.Lwc_pdone_a0:
	v_cndmask_b32_e64 v14, v8, v6, s[12:13]
	v_cmp_gt_u32_e32 vcc, s14, v4
	s_nop 1
	v_cndmask_b32_e32 v14, 0, v14, vcc
	v_cndmask_b32_e64 v15, v9, v7, s[12:13]
	v_cmp_gt_u32_e32 vcc, s14, v5
	s_nop 1
	v_cndmask_b32_e32 v15, 0, v15, vcc
	global_load_dwordx4 v[48:51], v10, s[8:9]
	global_load_dwordx4 v[68:71], v11, s[8:9]
	v_add_u32_e32 v122, 0, v2
	v_mad_u32_u24 v16, v122, s10, v14
	v_add_u32_e32 v122, 1, v2
	v_mad_u32_u24 v17, v122, s10, v14
	v_add_u32_e32 v122, 2, v2
	v_mad_u32_u24 v18, v122, s10, v14
	v_add_u32_e32 v122, 3, v2
	v_mad_u32_u24 v19, v122, s10, v14
	global_load_dwordx4 v[32:35], v16, s[2:3] nt
	global_load_dwordx4 v[36:39], v17, s[2:3] nt
	global_load_dwordx4 v[40:43], v18, s[2:3] nt
	global_load_dwordx4 v[44:47], v19, s[2:3] nt
	v_add_u32_e32 v122, 0, v3
	v_mad_u32_u24 v20, v122, s10, v15
	v_add_u32_e32 v122, 1, v3
	v_mad_u32_u24 v21, v122, s10, v15
	v_add_u32_e32 v122, 2, v3
	v_mad_u32_u24 v22, v122, s10, v15
	v_add_u32_e32 v122, 3, v3
	v_mad_u32_u24 v23, v122, s10, v15
	global_load_dwordx4 v[52:55], v20, s[2:3] nt
	global_load_dwordx4 v[56:59], v21, s[2:3] nt
	global_load_dwordx4 v[60:63], v22, s[2:3] nt
	global_load_dwordx4 v[64:67], v23, s[2:3] nt
.Lwc_top:
	s_mov_b64 s[16:17], s[6:7]
	s_mov_b32 s19, s11
	s_mov_b32 s20, s14
	s_mov_b32 s32, s15
	s_add_u32 s35, s35, 0x100
	s_cmpk_lt_u32 s35, 0x9d0
	s_cbranch_scc0 .Lwc_lastA
	s_cmpk_lt_u32 s35, 0x580
	s_cbranch_scc0 .Lwc_p1_b
	s_mov_b32 s21, 0
	s_mov_b32 s22, s35
	s_cmpk_lt_u32 s22, 0x160
	s_cbranch_scc1 .Lwc_gu_b
	s_sub_u32 s22, s22, 0x160
	s_add_u32 s21, s21, 1
	s_cmpk_lt_u32 s22, 0x160
	s_cbranch_scc1 .Lwc_gu_b
	s_sub_u32 s22, s22, 0x160
	s_add_u32 s21, s21, 1
	s_cmpk_lt_u32 s22, 0x160
	s_cbranch_scc1 .Lwc_gu_b
	s_sub_u32 s22, s22, 0x160
	s_add_u32 s21, s21, 1

; __device__ __forceinline__ unsigned cvt_pk_bf16(float lo, float hi) { unsigned r; asm volatile("v_cvt_pk_bf16_f32 %0, %1, %2" : "=v"(r) : "v"(lo), "v"(hi)); return r; }
; __device__ __forceinline__ void convert_weight_v4(LAS unsigned char* lds, const float* W, bf16_t* Bt, int K, int Nsrc, int Ndst, const float* gain, int mode) {
;     ...
; #pragma unroll
;         for (int i = 0; i < 8; ++i) {
;             const int e = tid + i * 512, kk = e >> 6, n4 = e & 63;
;             const float g = gain ? gain[k0 + kk] : 1.0f;
; #pragma unroll
;             for (int j = 0; j < 4; ++j) tile[kk * 257 + n4 * 4 + j] = v[i][j] * g;
;         }
;         __syncthreads();
; #pragma unroll
;         for (int i = 0; i < 8; ++i) {
;             const int e = tid + i * 512, nn = e >> 4, kq = e & 15;
;             u32x2 w; w.x = cvt_pk_bf16(tile[(4 * kq) * 257 + nn], tile[(4 * kq + 1) * 257 + nn]); w.y = cvt_pk_bf16(tile[(4 * kq + 2) * 257 + nn], tile[(4 * kq + 3) * 257 + nn]);
;             *(u32x2*)(Bt + (size_t)(n0 + nn) * K + k0 + 4 * kq) = w;
;         }
.Lwc_pdone_b:
	v_cndmask_b32_e64 v14, v8, v6, s[12:13]
	v_cmp_gt_u32_e32 vcc, s14, v4
	s_nop 1
	v_cndmask_b32_e32 v14, 0, v14, vcc
	v_cndmask_b32_e64 v15, v9, v7, s[12:13]
	v_cmp_gt_u32_e32 vcc, s14, v5
	s_nop 1
	v_cndmask_b32_e32 v15, 0, v15, vcc
	global_load_dwordx4 v[88:91], v10, s[8:9]
	global_load_dwordx4 v[108:111], v11, s[8:9]
	v_add_u32_e32 v122, 0, v2
	v_mad_u32_u24 v16, v122, s10, v14
	v_add_u32_e32 v122, 1, v2
	v_mad_u32_u24 v17, v122, s10, v14
	v_add_u32_e32 v122, 2, v2
	v_mad_u32_u24 v18, v122, s10, v14
	v_add_u32_e32 v122, 3, v2
	v_mad_u32_u24 v19, v122, s10, v14
	global_load_dwordx4 v[72:75], v16, s[2:3] nt
	global_load_dwordx4 v[76:79], v17, s[2:3] nt
	global_load_dwordx4 v[80:83], v18, s[2:3] nt
	global_load_dwordx4 v[84:87], v19, s[2:3] nt
	v_add_u32_e32 v122, 0, v3
	v_mad_u32_u24 v20, v122, s10, v15
	v_add_u32_e32 v122, 1, v3
	v_mad_u32_u24 v21, v122, s10, v15
	v_add_u32_e32 v122, 2, v3
	v_mad_u32_u24 v22, v122, s10, v15
	v_add_u32_e32 v122, 3, v3
	v_mad_u32_u24 v23, v122, s10, v15
	global_load_dwordx4 v[92:95], v20, s[2:3] nt
	global_load_dwordx4 v[96:99], v21, s[2:3] nt
	global_load_dwordx4 v[100:103], v22, s[2:3] nt
	global_load_dwordx4 v[104:107], v23, s[2:3] nt
	s_waitcnt vmcnt(10)
	s_cmp_eq_u32 s32, 0
	s_cbranch_scc0 .Lwc_g_A
	v_mov_b32_e32 v48, 1.0
	v_mov_b32_e32 v49, 1.0
	v_mov_b32_e32 v50, 1.0
	v_mov_b32_e32 v51, 1.0
	v_mov_b32_e32 v68, 1.0
	v_mov_b32_e32 v69, 1.0
	v_mov_b32_e32 v70, 1.0
	v_mov_b32_e32 v71, 1.0
.Lwc_g_A:
	s_cmp_eq_u32 s20, 0x7fffffff
	s_cbranch_scc1 .Lwc_nz_A
	v_cmp_gt_u32_e32 vcc, s20, v4
	s_nop 1
	v_cndmask_b32_e32 v32, 0, v32, vcc
	v_cndmask_b32_e32 v33, 0, v33, vcc
	v_cndmask_b32_e32 v34, 0, v34, vcc
	v_cndmask_b32_e32 v35, 0, v35, vcc
	v_cndmask_b32_e32 v36, 0, v36, vcc
	v_cndmask_b32_e32 v37, 0, v37, vcc
	v_cndmask_b32_e32 v38, 0, v38, vcc
	v_cndmask_b32_e32 v39, 0, v39, vcc
	v_cndmask_b32_e32 v40, 0, v40, vcc
	v_cndmask_b32_e32 v41, 0, v41, vcc
	v_cndmask_b32_e32 v42, 0, v42, vcc
	v_cndmask_b32_e32 v43, 0, v43, vcc
	v_cndmask_b32_e32 v44, 0, v44, vcc
	v_cndmask_b32_e32 v45, 0, v45, vcc
	v_cndmask_b32_e32 v46, 0, v46, vcc
	v_cndmask_b32_e32 v47, 0, v47, vcc
	v_cmp_gt_u32_e32 vcc, s20, v5
	s_nop 1
	v_cndmask_b32_e32 v52, 0, v52, vcc
	v_cndmask_b32_e32 v53, 0, v53, vcc
	v_cndmask_b32_e32 v54, 0, v54, vcc
	v_cndmask_b32_e32 v55, 0, v55, vcc
	v_cndmask_b32_e32 v56, 0, v56, vcc
	v_cndmask_b32_e32 v57, 0, v57, vcc
	v_cndmask_b32_e32 v58, 0, v58, vcc
	v_cndmask_b32_e32 v59, 0, v59, vcc
	v_cndmask_b32_e32 v60, 0, v60, vcc
	v_cndmask_b32_e32 v61, 0, v61, vcc
	v_cndmask_b32_e32 v62, 0, v62, vcc
	v_cndmask_b32_e32 v63, 0, v63, vcc
	v_cndmask_b32_e32 v64, 0, v64, vcc
	v_cndmask_b32_e32 v65, 0, v65, vcc
	v_cndmask_b32_e32 v66, 0, v66, vcc
	v_cndmask_b32_e32 v67, 0, v67, vcc
.Lwc_nz_A:
	v_mul_f32_e32 v32, v32, v48
	v_mul_f32_e32 v33, v33, v48
	v_mul_f32_e32 v34, v34, v48
	v_mul_f32_e32 v35, v35, v48
	v_mul_f32_e32 v36, v36, v49
	v_mul_f32_e32 v37, v37, v49
	v_mul_f32_e32 v38, v38, v49
	v_mul_f32_e32 v39, v39, v49
	v_mul_f32_e32 v40, v40, v50
	v_mul_f32_e32 v41, v41, v50
	v_mul_f32_e32 v42, v42, v50
	v_mul_f32_e32 v43, v43, v50
	v_mul_f32_e32 v44, v44, v51
	v_mul_f32_e32 v45, v45, v51
	v_mul_f32_e32 v46, v46, v51
	v_mul_f32_e32 v47, v47, v51
	v_add_u32_e32 v122, 0, v4
	v_mad_u32_u24 v24, v122, s19, v12
	v_add_u32_e32 v122, 1, v4
	v_mad_u32_u24 v25, v122, s19, v12
	v_add_u32_e32 v122, 2, v4
	v_mad_u32_u24 v26, v122, s19, v12
	v_add_u32_e32 v122, 3, v4
	v_mad_u32_u24 v27, v122, s19, v12
	v_cvt_pk_bf16_f32 v112, v32, v36
	v_cvt_pk_bf16_f32 v113, v40, v44
	global_store_dwordx2 v24, v[112:113], s[16:17]
	v_cvt_pk_bf16_f32 v114, v33, v37
	v_cvt_pk_bf16_f32 v115, v41, v45
	global_store_dwordx2 v25, v[114:115], s[16:17]
	v_cvt_pk_bf16_f32 v116, v34, v38
	v_cvt_pk_bf16_f32 v117, v42, v46
	global_store_dwordx2 v26, v[116:117], s[16:17]
	v_cvt_pk_bf16_f32 v118, v35, v39
	v_cvt_pk_bf16_f32 v119, v43, v47
	global_store_dwordx2 v27, v[118:119], s[16:17]
	s_nop 1
	v_mul_f32_e32 v52, v52, v68
	v_mul_f32_e32 v53, v53, v68
	v_mul_f32_e32 v54, v54, v68
	v_mul_f32_e32 v55, v55, v68
	v_mul_f32_e32 v56, v56, v69
	v_mul_f32_e32 v57, v57, v69
	v_mul_f32_e32 v58, v58, v69
	v_mul_f32_e32 v59, v59, v69
	v_mul_f32_e32 v60, v60, v70
	v_mul_f32_e32 v61, v61, v70
	v_mul_f32_e32 v62, v62, v70
	v_mul_f32_e32 v63, v63, v70
	v_mul_f32_e32 v64, v64, v71
	v_mul_f32_e32 v65, v65, v71
	v_mul_f32_e32 v66, v66, v71
	v_mul_f32_e32 v67, v67, v71
	v_add_u32_e32 v122, 0, v5
	v_mad_u32_u24 v28, v122, s19, v13
	v_add_u32_e32 v122, 1, v5
	v_mad_u32_u24 v29, v122, s19, v13
	v_add_u32_e32 v122, 2, v5
	v_mad_u32_u24 v30, v122, s19, v13
	v_add_u32_e32 v122, 3, v5
	v_mad_u32_u24 v31, v122, s19, v13
	v_cvt_pk_bf16_f32 v112, v52, v56
	v_cvt_pk_bf16_f32 v113, v60, v64
	global_store_dwordx2 v28, v[112:113], s[16:17]
	v_cvt_pk_bf16_f32 v114, v53, v57
	v_cvt_pk_bf16_f32 v115, v61, v65
	global_store_dwordx2 v29, v[114:115], s[16:17]
	v_cvt_pk_bf16_f32 v116, v54, v58
	v_cvt_pk_bf16_f32 v117, v62, v66
	global_store_dwordx2 v30, v[116:117], s[16:17]
	v_cvt_pk_bf16_f32 v118, v55, v59
	v_cvt_pk_bf16_f32 v119, v63, v67
	global_store_dwordx2 v31, v[118:119], s[16:17]
	s_mov_b64 s[16:17], s[6:7]
	s_mov_b32 s19, s11
	s_mov_b32 s20, s14
	s_mov_b32 s32, s15
	s_add_u32 s35, s35, 0x100
	s_cmpk_lt_u32 s35, 0x9d0
	s_cbranch_scc0 .Lwc_lastB
	s_cmpk_lt_u32 s35, 0x580
	s_cbranch_scc0 .Lwc_p1_a
	s_mov_b32 s21, 0
	s_mov_b32 s22, s35
	s_cmpk_lt_u32 s22, 0x160
	s_cbranch_scc1 .Lwc_gu_a
	s_sub_u32 s22, s22, 0x160
	s_add_u32 s21, s21, 1
	s_cmpk_lt_u32 s22, 0x160
	s_cbranch_scc1 .Lwc_gu_a
	s_sub_u32 s22, s22, 0x160
	s_add_u32 s21, s21, 1
	s_cmpk_lt_u32 s22, 0x160
	s_cbranch_scc1 .Lwc_gu_a
	s_sub_u32 s22, s22, 0x160
	s_add_u32 s21, s21, 1

; __device__ __forceinline__ unsigned cvt_pk_bf16(float lo, float hi) { unsigned r; asm volatile("v_cvt_pk_bf16_f32 %0, %1, %2" : "=v"(r) : "v"(lo), "v"(hi)); return r; }
; __device__ __forceinline__ void convert_weight_v4(LAS unsigned char* lds, const float* W, bf16_t* Bt, int K, int Nsrc, int Ndst, const float* gain, int mode) {
;     ...
; #pragma unroll
;         for (int i = 0; i < 8; ++i) {
;             const int e = tid + i * 512, kk = e >> 6, n4 = e & 63;
;             const float g = gain ? gain[k0 + kk] : 1.0f;
; #pragma unroll
;             for (int j = 0; j < 4; ++j) tile[kk * 257 + n4 * 4 + j] = v[i][j] * g;
;         }
;         __syncthreads();
; #pragma unroll
;         for (int i = 0; i < 8; ++i) {
;             const int e = tid + i * 512, nn = e >> 4, kq = e & 15;
;             u32x2 w; w.x = cvt_pk_bf16(tile[(4 * kq) * 257 + nn], tile[(4 * kq + 1) * 257 + nn]); w.y = cvt_pk_bf16(tile[(4 * kq + 2) * 257 + nn], tile[(4 * kq + 3) * 257 + nn]);
;             *(u32x2*)(Bt + (size_t)(n0 + nn) * K + k0 + 4 * kq) = w;
;         }
.Lwc_pdone_a:
	v_cndmask_b32_e64 v14, v8, v6, s[12:13]
	v_cmp_gt_u32_e32 vcc, s14, v4
	s_nop 1
	v_cndmask_b32_e32 v14, 0, v14, vcc
	v_cndmask_b32_e64 v15, v9, v7, s[12:13]
	v_cmp_gt_u32_e32 vcc, s14, v5
	s_nop 1
	v_cndmask_b32_e32 v15, 0, v15, vcc
	global_load_dwordx4 v[48:51], v10, s[8:9]
	global_load_dwordx4 v[68:71], v11, s[8:9]
	v_add_u32_e32 v122, 0, v2
	v_mad_u32_u24 v16, v122, s10, v14
	v_add_u32_e32 v122, 1, v2
	v_mad_u32_u24 v17, v122, s10, v14
	v_add_u32_e32 v122, 2, v2
	v_mad_u32_u24 v18, v122, s10, v14
	v_add_u32_e32 v122, 3, v2
	v_mad_u32_u24 v19, v122, s10, v14
	global_load_dwordx4 v[32:35], v16, s[2:3] nt
	global_load_dwordx4 v[36:39], v17, s[2:3] nt
	global_load_dwordx4 v[40:43], v18, s[2:3] nt
	global_load_dwordx4 v[44:47], v19, s[2:3] nt
	v_add_u32_e32 v122, 0, v3
	v_mad_u32_u24 v20, v122, s10, v15
	v_add_u32_e32 v122, 1, v3
	v_mad_u32_u24 v21, v122, s10, v15
	v_add_u32_e32 v122, 2, v3
	v_mad_u32_u24 v22, v122, s10, v15
	v_add_u32_e32 v122, 3, v3
	v_mad_u32_u24 v23, v122, s10, v15
	global_load_dwordx4 v[52:55], v20, s[2:3] nt
	global_load_dwordx4 v[56:59], v21, s[2:3] nt
	global_load_dwordx4 v[60:63], v22, s[2:3] nt
	global_load_dwordx4 v[64:67], v23, s[2:3] nt
	s_waitcnt vmcnt(10)
	s_cmp_eq_u32 s32, 0
	s_cbranch_scc0 .Lwc_g_B
	v_mov_b32_e32 v88, 1.0
	v_mov_b32_e32 v89, 1.0
	v_mov_b32_e32 v90, 1.0
	v_mov_b32_e32 v91, 1.0
	v_mov_b32_e32 v108, 1.0
	v_mov_b32_e32 v109, 1.0
	v_mov_b32_e32 v110, 1.0
	v_mov_b32_e32 v111, 1.0
.Lwc_g_B:
	s_cmp_eq_u32 s20, 0x7fffffff
	s_cbranch_scc1 .Lwc_nz_B
	v_cmp_gt_u32_e32 vcc, s20, v4
	s_nop 1
	v_cndmask_b32_e32 v72, 0, v72, vcc
	v_cndmask_b32_e32 v73, 0, v73, vcc
	v_cndmask_b32_e32 v74, 0, v74, vcc
	v_cndmask_b32_e32 v75, 0, v75, vcc
	v_cndmask_b32_e32 v76, 0, v76, vcc
	v_cndmask_b32_e32 v77, 0, v77, vcc
	v_cndmask_b32_e32 v78, 0, v78, vcc
	v_cndmask_b32_e32 v79, 0, v79, vcc
	v_cndmask_b32_e32 v80, 0, v80, vcc
	v_cndmask_b32_e32 v81, 0, v81, vcc
	v_cndmask_b32_e32 v82, 0, v82, vcc
	v_cndmask_b32_e32 v83, 0, v83, vcc
	v_cndmask_b32_e32 v84, 0, v84, vcc
	v_cndmask_b32_e32 v85, 0, v85, vcc
	v_cndmask_b32_e32 v86, 0, v86, vcc
	v_cndmask_b32_e32 v87, 0, v87, vcc
	v_cmp_gt_u32_e32 vcc, s20, v5
	s_nop 1
	v_cndmask_b32_e32 v92, 0, v92, vcc
	v_cndmask_b32_e32 v93, 0, v93, vcc
	v_cndmask_b32_e32 v94, 0, v94, vcc
	v_cndmask_b32_e32 v95, 0, v95, vcc
	v_cndmask_b32_e32 v96, 0, v96, vcc
	v_cndmask_b32_e32 v97, 0, v97, vcc
	v_cndmask_b32_e32 v98, 0, v98, vcc
	v_cndmask_b32_e32 v99, 0, v99, vcc
	v_cndmask_b32_e32 v100, 0, v100, vcc
	v_cndmask_b32_e32 v101, 0, v101, vcc
	v_cndmask_b32_e32 v102, 0, v102, vcc
	v_cndmask_b32_e32 v103, 0, v103, vcc
	v_cndmask_b32_e32 v104, 0, v104, vcc
	v_cndmask_b32_e32 v105, 0, v105, vcc
	v_cndmask_b32_e32 v106, 0, v106, vcc
	v_cndmask_b32_e32 v107, 0, v107, vcc
.Lwc_nz_B:
	v_mul_f32_e32 v72, v72, v88
	v_mul_f32_e32 v73, v73, v88
	v_mul_f32_e32 v74, v74, v88
	v_mul_f32_e32 v75, v75, v88
	v_mul_f32_e32 v76, v76, v89
	v_mul_f32_e32 v77, v77, v89
	v_mul_f32_e32 v78, v78, v89
	v_mul_f32_e32 v79, v79, v89
	v_mul_f32_e32 v80, v80, v90
	v_mul_f32_e32 v81, v81, v90
	v_mul_f32_e32 v82, v82, v90
	v_mul_f32_e32 v83, v83, v90
	v_mul_f32_e32 v84, v84, v91
	v_mul_f32_e32 v85, v85, v91
	v_mul_f32_e32 v86, v86, v91
	v_mul_f32_e32 v87, v87, v91
	v_add_u32_e32 v122, 0, v4
	v_mad_u32_u24 v24, v122, s19, v12
	v_add_u32_e32 v122, 1, v4
	v_mad_u32_u24 v25, v122, s19, v12
	v_add_u32_e32 v122, 2, v4
	v_mad_u32_u24 v26, v122, s19, v12
	v_add_u32_e32 v122, 3, v4
	v_mad_u32_u24 v27, v122, s19, v12
	v_cvt_pk_bf16_f32 v112, v72, v76
	v_cvt_pk_bf16_f32 v113, v80, v84
	global_store_dwordx2 v24, v[112:113], s[16:17]
	v_cvt_pk_bf16_f32 v114, v73, v77
	v_cvt_pk_bf16_f32 v115, v81, v85
	global_store_dwordx2 v25, v[114:115], s[16:17]
	v_cvt_pk_bf16_f32 v116, v74, v78
	v_cvt_pk_bf16_f32 v117, v82, v86
	global_store_dwordx2 v26, v[116:117], s[16:17]
	v_cvt_pk_bf16_f32 v118, v75, v79
	v_cvt_pk_bf16_f32 v119, v83, v87
	global_store_dwordx2 v27, v[118:119], s[16:17]
	s_nop 1
	v_mul_f32_e32 v92, v92, v108
	v_mul_f32_e32 v93, v93, v108
	v_mul_f32_e32 v94, v94, v108
	v_mul_f32_e32 v95, v95, v108
	v_mul_f32_e32 v96, v96, v109
	v_mul_f32_e32 v97, v97, v109
	v_mul_f32_e32 v98, v98, v109
	v_mul_f32_e32 v99, v99, v109
	v_mul_f32_e32 v100, v100, v110
	v_mul_f32_e32 v101, v101, v110
	v_mul_f32_e32 v102, v102, v110
	v_mul_f32_e32 v103, v103, v110
	v_mul_f32_e32 v104, v104, v111
	v_mul_f32_e32 v105, v105, v111
	v_mul_f32_e32 v106, v106, v111
	v_mul_f32_e32 v107, v107, v111
	v_add_u32_e32 v122, 0, v5
	v_mad_u32_u24 v28, v122, s19, v13
	v_add_u32_e32 v122, 1, v5
	v_mad_u32_u24 v29, v122, s19, v13
	v_add_u32_e32 v122, 2, v5
	v_mad_u32_u24 v30, v122, s19, v13
	v_add_u32_e32 v122, 3, v5
	v_mad_u32_u24 v31, v122, s19, v13
	v_cvt_pk_bf16_f32 v112, v92, v96
	v_cvt_pk_bf16_f32 v113, v100, v104
	global_store_dwordx2 v28, v[112:113], s[16:17]
	v_cvt_pk_bf16_f32 v114, v93, v97
	v_cvt_pk_bf16_f32 v115, v101, v105
	global_store_dwordx2 v29, v[114:115], s[16:17]
	v_cvt_pk_bf16_f32 v116, v94, v98
	v_cvt_pk_bf16_f32 v117, v102, v106
	global_store_dwordx2 v30, v[116:117], s[16:17]
	v_cvt_pk_bf16_f32 v118, v95, v99
	v_cvt_pk_bf16_f32 v119, v103, v107
	global_store_dwordx2 v31, v[118:119], s[16:17]
	s_branch .Lwc_top
.Lwc_lastA:
	s_waitcnt vmcnt(0)
	s_cmp_eq_u32 s32, 0
	s_cbranch_scc0 .Lwc_g_A2
	v_mov_b32_e32 v48, 1.0
	v_mov_b32_e32 v49, 1.0
	v_mov_b32_e32 v50, 1.0
	v_mov_b32_e32 v51, 1.0
	v_mov_b32_e32 v68, 1.0
	v_mov_b32_e32 v69, 1.0
	v_mov_b32_e32 v70, 1.0
	v_mov_b32_e32 v71, 1.0

; __device__ __forceinline__ unsigned cvt_pk_bf16(float lo, float hi) { unsigned r; asm volatile("v_cvt_pk_bf16_f32 %0, %1, %2" : "=v"(r) : "v"(lo), "v"(hi)); return r; }
; __device__ __forceinline__ void convert_weight_v4(LAS unsigned char* lds, const float* W, bf16_t* Bt, int K, int Nsrc, int Ndst, const float* gain, int mode) {
;     ...
; #pragma unroll
;         for (int i = 0; i < 8; ++i) {
;             const int e = tid + i * 512, kk = e >> 6, n4 = e & 63;
;             const float g = gain ? gain[k0 + kk] : 1.0f;
; #pragma unroll
;             for (int j = 0; j < 4; ++j) tile[kk * 257 + n4 * 4 + j] = v[i][j] * g;
;         }
;         __syncthreads();
; #pragma unroll
;         for (int i = 0; i < 8; ++i) {
;             const int e = tid + i * 512, nn = e >> 4, kq = e & 15;
;             u32x2 w; w.x = cvt_pk_bf16(tile[(4 * kq) * 257 + nn], tile[(4 * kq + 1) * 257 + nn]); w.y = cvt_pk_bf16(tile[(4 * kq + 2) * 257 + nn], tile[(4 * kq + 3) * 257 + nn]);
;             *(u32x2*)(Bt + (size_t)(n0 + nn) * K + k0 + 4 * kq) = w;
;         }
.Lwc_nz_A2:
	v_mul_f32_e32 v32, v32, v48
	v_mul_f32_e32 v33, v33, v48
	v_mul_f32_e32 v34, v34, v48
	v_mul_f32_e32 v35, v35, v48
	v_mul_f32_e32 v36, v36, v49
	v_mul_f32_e32 v37, v37, v49
	v_mul_f32_e32 v38, v38, v49
	v_mul_f32_e32 v39, v39, v49
	v_mul_f32_e32 v40, v40, v50
	v_mul_f32_e32 v41, v41, v50
	v_mul_f32_e32 v42, v42, v50
	v_mul_f32_e32 v43, v43, v50
	v_mul_f32_e32 v44, v44, v51
	v_mul_f32_e32 v45, v45, v51
	v_mul_f32_e32 v46, v46, v51
	v_mul_f32_e32 v47, v47, v51
	v_add_u32_e32 v122, 0, v4
	v_mad_u32_u24 v24, v122, s19, v12
	v_add_u32_e32 v122, 1, v4
	v_mad_u32_u24 v25, v122, s19, v12
	v_add_u32_e32 v122, 2, v4
	v_mad_u32_u24 v26, v122, s19, v12
	v_add_u32_e32 v122, 3, v4
	v_mad_u32_u24 v27, v122, s19, v12
	v_cvt_pk_bf16_f32 v112, v32, v36
	v_cvt_pk_bf16_f32 v113, v40, v44
	global_store_dwordx2 v24, v[112:113], s[16:17]
	v_cvt_pk_bf16_f32 v114, v33, v37
	v_cvt_pk_bf16_f32 v115, v41, v45
	global_store_dwordx2 v25, v[114:115], s[16:17]
	v_cvt_pk_bf16_f32 v116, v34, v38
	v_cvt_pk_bf16_f32 v117, v42, v46
	global_store_dwordx2 v26, v[116:117], s[16:17]
	v_cvt_pk_bf16_f32 v118, v35, v39
	v_cvt_pk_bf16_f32 v119, v43, v47
	global_store_dwordx2 v27, v[118:119], s[16:17]
	s_nop 1
	v_mul_f32_e32 v52, v52, v68
	v_mul_f32_e32 v53, v53, v68
	v_mul_f32_e32 v54, v54, v68
	v_mul_f32_e32 v55, v55, v68
	v_mul_f32_e32 v56, v56, v69
	v_mul_f32_e32 v57, v57, v69
	v_mul_f32_e32 v58, v58, v69
	v_mul_f32_e32 v59, v59, v69
	v_mul_f32_e32 v60, v60, v70
	v_mul_f32_e32 v61, v61, v70
	v_mul_f32_e32 v62, v62, v70
	v_mul_f32_e32 v63, v63, v70
	v_mul_f32_e32 v64, v64, v71
	v_mul_f32_e32 v65, v65, v71
	v_mul_f32_e32 v66, v66, v71
	v_mul_f32_e32 v67, v67, v71
	v_add_u32_e32 v122, 0, v5
	v_mad_u32_u24 v28, v122, s19, v13
	v_add_u32_e32 v122, 1, v5
	v_mad_u32_u24 v29, v122, s19, v13
	v_add_u32_e32 v122, 2, v5
	v_mad_u32_u24 v30, v122, s19, v13
	v_add_u32_e32 v122, 3, v5
	v_mad_u32_u24 v31, v122, s19, v13
	v_cvt_pk_bf16_f32 v112, v52, v56
	v_cvt_pk_bf16_f32 v113, v60, v64
	global_store_dwordx2 v28, v[112:113], s[16:17]
	v_cvt_pk_bf16_f32 v114, v53, v57
	v_cvt_pk_bf16_f32 v115, v61, v65
	global_store_dwordx2 v29, v[114:115], s[16:17]
	v_cvt_pk_bf16_f32 v116, v54, v58
	v_cvt_pk_bf16_f32 v117, v62, v66
	global_store_dwordx2 v30, v[116:117], s[16:17]
	v_cvt_pk_bf16_f32 v118, v55, v59
	v_cvt_pk_bf16_f32 v119, v63, v67
	global_store_dwordx2 v31, v[118:119], s[16:17]
	s_branch .Lwc_done
.Lwc_lastB:
	s_waitcnt vmcnt(0)
	s_cmp_eq_u32 s32, 0
	s_cbranch_scc0 .Lwc_g_B2
	v_mov_b32_e32 v88, 1.0
	v_mov_b32_e32 v89, 1.0
	v_mov_b32_e32 v90, 1.0
	v_mov_b32_e32 v91, 1.0
	v_mov_b32_e32 v108, 1.0
	v_mov_b32_e32 v109, 1.0
	v_mov_b32_e32 v110, 1.0
	v_mov_b32_e32 v111, 1.0

; __device__ __forceinline__ unsigned cvt_pk_bf16(float lo, float hi) { unsigned r; asm volatile("v_cvt_pk_bf16_f32 %0, %1, %2" : "=v"(r) : "v"(lo), "v"(hi)); return r; }
; __device__ __forceinline__ void convert_weight_v4(LAS unsigned char* lds, const float* W, bf16_t* Bt, int K, int Nsrc, int Ndst, const float* gain, int mode) {
;     ...
; #pragma unroll
;         for (int i = 0; i < 8; ++i) {
;             const int e = tid + i * 512, kk = e >> 6, n4 = e & 63;
;             const float g = gain ? gain[k0 + kk] : 1.0f;
; #pragma unroll
;             for (int j = 0; j < 4; ++j) tile[kk * 257 + n4 * 4 + j] = v[i][j] * g;
;         }
;         __syncthreads();
; #pragma unroll
;         for (int i = 0; i < 8; ++i) {
;             const int e = tid + i * 512, nn = e >> 4, kq = e & 15;
;             u32x2 w; w.x = cvt_pk_bf16(tile[(4 * kq) * 257 + nn], tile[(4 * kq + 1) * 257 + nn]); w.y = cvt_pk_bf16(tile[(4 * kq + 2) * 257 + nn], tile[(4 * kq + 3) * 257 + nn]);
;             *(u32x2*)(Bt + (size_t)(n0 + nn) * K + k0 + 4 * kq) = w;
;         }
; __device__ __forceinline__ void prologue(LAS unsigned char* lds, const Params& P) {
;     ...
;     for (int l = 0; l < 2; ++l) {
;         convert_weight_v4(lds, in[10] + (size_t)l * D * 2 * FF, (bf16_t*)(ws + W_GU + (size_t)(l * 2 + 0) * W_GU_SZ), D, 2 * FF, 2 * FF, in[9] + l * D, 1);
;         convert_weight_v4(lds, in[14] + (size_t)l * D * 2 * FF, (bf16_t*)(ws + W_GU + (size_t)(l * 2 + 1) * W_GU_SZ), D, 2 * FF, 2 * FF, in[13] + l * D, 1);
;         convert_weight_v4(lds, in[11] + (size_t)l * FF * D, (bf16_t*)(ws + W_DN + (size_t)(l * 2 + 0) * W_DN_SZ), FF, D, D, nullptr, 0);
;         convert_weight_v4(lds, in[15] + (size_t)l * FF * D, (bf16_t*)(ws + W_DN + (size_t)(l * 2 + 1) * W_DN_SZ), FF, D, D, nullptr, 0);
;     }
.Lwc_nz_B2:
	v_mul_f32_e32 v72, v72, v88
	v_mul_f32_e32 v73, v73, v88
	v_mul_f32_e32 v74, v74, v88
	v_mul_f32_e32 v75, v75, v88
	v_mul_f32_e32 v76, v76, v89
	v_mul_f32_e32 v77, v77, v89
	v_mul_f32_e32 v78, v78, v89
	v_mul_f32_e32 v79, v79, v89
	v_mul_f32_e32 v80, v80, v90
	v_mul_f32_e32 v81, v81, v90
	v_mul_f32_e32 v82, v82, v90
	v_mul_f32_e32 v83, v83, v90
	v_mul_f32_e32 v84, v84, v91
	v_mul_f32_e32 v85, v85, v91
	v_mul_f32_e32 v86, v86, v91
	v_mul_f32_e32 v87, v87, v91
	v_add_u32_e32 v122, 0, v4
	v_mad_u32_u24 v24, v122, s19, v12
	v_add_u32_e32 v122, 1, v4
	v_mad_u32_u24 v25, v122, s19, v12
	v_add_u32_e32 v122, 2, v4
	v_mad_u32_u24 v26, v122, s19, v12
	v_add_u32_e32 v122, 3, v4
	v_mad_u32_u24 v27, v122, s19, v12
	v_cvt_pk_bf16_f32 v112, v72, v76
	v_cvt_pk_bf16_f32 v113, v80, v84
	global_store_dwordx2 v24, v[112:113], s[16:17]
	v_cvt_pk_bf16_f32 v114, v73, v77
	v_cvt_pk_bf16_f32 v115, v81, v85
	global_store_dwordx2 v25, v[114:115], s[16:17]
	v_cvt_pk_bf16_f32 v116, v74, v78
	v_cvt_pk_bf16_f32 v117, v82, v86
	global_store_dwordx2 v26, v[116:117], s[16:17]
	v_cvt_pk_bf16_f32 v118, v75, v79
	v_cvt_pk_bf16_f32 v119, v83, v87
	global_store_dwordx2 v27, v[118:119], s[16:17]
	s_nop 1
	v_mul_f32_e32 v92, v92, v108
	v_mul_f32_e32 v93, v93, v108
	v_mul_f32_e32 v94, v94, v108
	v_mul_f32_e32 v95, v95, v108
	v_mul_f32_e32 v96, v96, v109
	v_mul_f32_e32 v97, v97, v109
	v_mul_f32_e32 v98, v98, v109
	v_mul_f32_e32 v99, v99, v109
	v_mul_f32_e32 v100, v100, v110
	v_mul_f32_e32 v101, v101, v110
	v_mul_f32_e32 v102, v102, v110
	v_mul_f32_e32 v103, v103, v110
	v_mul_f32_e32 v104, v104, v111
	v_mul_f32_e32 v105, v105, v111
	v_mul_f32_e32 v106, v106, v111
	v_mul_f32_e32 v107, v107, v111
	v_add_u32_e32 v122, 0, v5
	v_mad_u32_u24 v28, v122, s19, v13
	v_add_u32_e32 v122, 1, v5
	v_mad_u32_u24 v29, v122, s19, v13
	v_add_u32_e32 v122, 2, v5
	v_mad_u32_u24 v30, v122, s19, v13
	v_add_u32_e32 v122, 3, v5
	v_mad_u32_u24 v31, v122, s19, v13
	v_cvt_pk_bf16_f32 v112, v92, v96
	v_cvt_pk_bf16_f32 v113, v100, v104
	global_store_dwordx2 v28, v[112:113], s[16:17]
	v_cvt_pk_bf16_f32 v114, v93, v97
	v_cvt_pk_bf16_f32 v115, v101, v105
	global_store_dwordx2 v29, v[114:115], s[16:17]
	v_cvt_pk_bf16_f32 v116, v94, v98
	v_cvt_pk_bf16_f32 v117, v102, v106
	global_store_dwordx2 v30, v[116:117], s[16:17]
	v_cvt_pk_bf16_f32 v118, v95, v99
	v_cvt_pk_bf16_f32 v119, v103, v107
	global_store_dwordx2 v31, v[118:119], s[16:17]
.Lwc_done:
	s_add_u32 s17, s88, 0x2c00000
	s_addc_u32 s19, s89, 0
	s_cmp_lg_u64 s[58:59], 0
	s_cselect_b64 s[6:7], -1, 0
	s_cmp_lg_u64 s[66:67], 0
	v_mov_b32_e32 v54, v254
	s_mov_b32 s16, s18
	s_mov_b64 s[10:11], -1
	s_cselect_b64 s[8:9], -1, 0
	s_movk_i32 s22, 0xb00
	s_movk_i32 s23, 0x404
	v_mov_b32_e32 v33, 0
	s_movk_i32 s24, 0x400
	s_movk_i32 s25, 0x5800
	v_cndmask_b32_e64 v55, 0, 1, s[6:7]
	s_movk_i32 s26, 0x1600
	s_mov_b32 s28, 0
	s_branch .LBB0_20

; #define LAS __attribute__((address_space(3)))
; __device__ __forceinline__ int opq_tid() { int t = threadIdx.x; asm volatile("" : "+v"(t)); return t; }
; __device__ __forceinline__ int opq_bid() { int b = blockIdx.x; asm volatile("" : "+s"(b)); return b; }
; __device__ __forceinline__ f32x4 ld_nt(const float* p) { return __builtin_nontemporal_load((const f32x4*)p); }
; __device__ __forceinline__ void convert_weight_v4(LAS unsigned char* lds, const float* W, bf16_t* Bt, int K, int Nsrc, int Ndst, const float* gain, int mode) {
;     LAS float* tile = (LAS float*)lds;
;     const int tid = opq_tid(), nkt = K / 64, nnt = Ndst / 256;
;     for (int t = opq_bid(); t < nkt * nnt; t += gridDim.x) {
;         const int k0 = (t % nkt) * 64, pn = t / nkt, n0 = pn * 256;
;         f32x4 v[8];
; #pragma unroll
;         for (int i = 0; i < 8; ++i) {
;             const int e = tid + i * 512, kk = e >> 6, n4 = e & 63;
;             const int n = (mode == 1) ? (n4 >> 5) * FF + pn * 128 + (n4 & 31) * 4 : n0 + n4 * 4;
;             v[i] = (f32x4){0.f, 0.f, 0.f, 0.f};
;             if (n < Nsrc) v[i] = ld_nt(W + (size_t)(k0 + kk) * Nsrc + n);
; __device__ __forceinline__ void prologue(LAS unsigned char* lds, const Params& P) {
;     ...
;     for (int l = 0; l < 2; ++l) {
;         convert_weight_v4(lds, in[10] + (size_t)l * D * 2 * FF, (bf16_t*)(ws + W_GU + (size_t)(l * 2 + 0) * W_GU_SZ), D, 2 * FF, 2 * FF, in[9] + l * D, 1);
.LBB0_20:
	s_lshl_b32 s29, s28, 1
	s_lshl_b32 s12, s28, 10
	v_mov_b32_e32 v0, v254
	s_movk_i32 s27, 0x7fff
	s_mul_i32 s4, s28, 0x580000
	s_cmpk_gt_i32 s27, 0x15f
	s_mov_b32 s13, s5
	s_cbranch_scc1 .LBB0_39
	s_lshl_b64 s[2:3], s[4:5], 2
	s_add_u32 s2, s60, s2
	s_addc_u32 s3, s61, s3
	s_lshl_b64 s[14:15], s[12:13], 2
	v_lshlrev_b32_e32 v2, 2, v0
	s_add_u32 s14, s58, s14
	v_bfe_i32 v1, v0, 5, 1
	v_and_b32_e32 v3, 0x7c, v2
	v_and_b32_e32 v2, 60, v2
	s_addc_u32 s15, s59, s15
	s_mul_i32 s20, s29, 0xb00000
	v_and_or_b32 v56, v1, s22, v3
	v_lshlrev_b32_e32 v1, 4, v0
	v_mad_u32_u24 v3, v2, s23, 0
	v_lshlrev_b32_e32 v32, 1, v2
	v_ashrrev_i32_e32 v57, 4, v0
	v_ashrrev_i32_e32 v59, 6, v0
	v_add_u32_e32 v2, 0x200, v0
	v_add_u32_e32 v4, 0x400, v0
	v_add_u32_e32 v5, 0x600, v0
	v_add_u32_e32 v6, 0x800, v0
	v_add_u32_e32 v7, 0xa00, v0
	v_add_u32_e32 v8, 0xc00, v0
	v_add_u32_e32 v0, 0xe00, v0
	s_add_u32 s20, s88, s20
	v_and_b32_e32 v1, 0x3f0, v1
	v_ashrrev_i32_e32 v60, 6, v2
	v_ashrrev_i32_e32 v61, 6, v4
	v_ashrrev_i32_e32 v62, 6, v5
	v_ashrrev_i32_e32 v63, 6, v6
	v_ashrrev_i32_e32 v64, 6, v7
	v_ashrrev_i32_e32 v65, 6, v8
	v_ashrrev_i32_e32 v66, 6, v0
	s_addc_u32 s21, s89, 0
	v_add_u32_e32 v1, 0, v1
	v_mul_lo_u32 v9, v59, s23
	v_mul_lo_u32 v10, v60, s23
	v_mul_lo_u32 v11, v61, s23
	v_mul_lo_u32 v12, v62, s23
	v_mul_lo_u32 v13, v63, s23
	v_mul_lo_u32 v14, v64, s23
	v_mul_lo_u32 v15, v65, s23
	v_mul_lo_u32 v16, v66, s23
	v_ashrrev_i32_e32 v67, 4, v2
	v_ashrrev_i32_e32 v69, 4, v4
	v_ashrrev_i32_e32 v71, 4, v5
	v_ashrrev_i32_e32 v73, 4, v6
	v_ashrrev_i32_e32 v75, 4, v7
	v_ashrrev_i32_e32 v77, 4, v8
	v_ashrrev_i32_e32 v79, 4, v0
	v_lshl_add_u64 v[34:35], s[20:21], 0, v[32:33]
	v_lshl_add_u32 v58, v57, 2, v3
	v_lshl_add_u32 v68, v67, 2, v3
	v_lshl_add_u32 v70, v69, 2, v3
	v_lshl_add_u32 v72, v71, 2, v3
	v_lshl_add_u32 v74, v73, 2, v3
	v_lshl_add_u32 v76, v75, 2, v3
	v_lshl_add_u32 v78, v77, 2, v3
	v_lshl_add_u32 v80, v79, 2, v3
	s_lshl_b32 s30, s27, 6
	s_lshl_b32 s31, s94, 6
	v_add_u32_e32 v81, v1, v10
	v_add_u32_e32 v82, v1, v12
	v_add_u32_e32 v83, v1, v14
	v_add_u32_e32 v84, v1, v16
	v_mov_b64_e32 v[36:37], s[2:3]
	v_add_u32_e32 v85, v1, v9
	v_add_u32_e32 v86, v1, v11
	v_add_u32_e32 v87, v1, v13
	v_add_u32_e32 v88, v1, v15
	s_branch .LBB0_24

; #define LAS __attribute__((address_space(3)))
; __device__ __forceinline__ int opq_tid() { int t = threadIdx.x; asm volatile("" : "+v"(t)); return t; }
; __device__ __forceinline__ int opq_bid() { int b = blockIdx.x; asm volatile("" : "+s"(b)); return b; }
; __device__ __forceinline__ f32x4 ld_nt(const float* p) { return __builtin_nontemporal_load((const f32x4*)p); }
; __device__ __forceinline__ void convert_weight_v4(LAS unsigned char* lds, const float* W, bf16_t* Bt, int K, int Nsrc, int Ndst, const float* gain, int mode) {
;     LAS float* tile = (LAS float*)lds;
;     const int tid = opq_tid(), nkt = K / 64, nnt = Ndst / 256;
;     for (int t = opq_bid(); t < nkt * nnt; t += gridDim.x) {
;         const int k0 = (t % nkt) * 64, pn = t / nkt, n0 = pn * 256;
;         f32x4 v[8];
; #pragma unroll
;         for (int i = 0; i < 8; ++i) {
;             const int e = tid + i * 512, kk = e >> 6, n4 = e & 63;
;             const int n = (mode == 1) ? (n4 >> 5) * FF + pn * 128 + (n4 & 31) * 4 : n0 + n4 * 4;
;             v[i] = (f32x4){0.f, 0.f, 0.f, 0.f};
;             if (n < Nsrc) v[i] = ld_nt(W + (size_t)(k0 + kk) * Nsrc + n);
; __device__ __forceinline__ void prologue(LAS unsigned char* lds, const Params& P) {
;     ...
;         convert_weight_v4(lds, in[14] + (size_t)l * D * 2 * FF, (bf16_t*)(ws + W_GU + (size_t)(l * 2 + 1) * W_GU_SZ), D, 2 * FF, 2 * FF, in[13] + l * D, 1);
.LBB0_39:
	s_or_b32 s27, s29, 1
	v_mov_b32_e32 v0, v254
	s_movk_i32 s30, 0x7fff
	s_cmpk_gt_i32 s30, 0x15f
	s_cbranch_scc1 .LBB0_58
	s_lshl_b64 s[2:3], s[4:5], 2
	s_add_u32 s14, s68, s2
	s_addc_u32 s15, s69, s3
	s_lshl_b64 s[2:3], s[12:13], 2
	v_lshlrev_b32_e32 v2, 2, v0
	s_add_u32 s12, s66, s2
	v_bfe_i32 v1, v0, 5, 1
	v_and_b32_e32 v3, 0x7c, v2
	v_and_b32_e32 v2, 60, v2
	s_addc_u32 s13, s67, s3
	s_mul_i32 s2, s27, 0xb00000
	v_and_or_b32 v52, v1, s22, v3
	v_lshlrev_b32_e32 v1, 4, v0
	v_mad_u32_u24 v3, v2, s23, 0
	v_lshlrev_b32_e32 v32, 1, v2
	v_ashrrev_i32_e32 v53, 4, v0
	v_ashrrev_i32_e32 v57, 6, v0
	v_add_u32_e32 v2, 0x200, v0
	v_add_u32_e32 v4, 0x400, v0
	v_add_u32_e32 v5, 0x600, v0
	v_add_u32_e32 v6, 0x800, v0
	v_add_u32_e32 v7, 0xa00, v0
	v_add_u32_e32 v8, 0xc00, v0
	v_add_u32_e32 v0, 0xe00, v0
	s_add_u32 s2, s88, s2
	v_and_b32_e32 v1, 0x3f0, v1
	v_ashrrev_i32_e32 v58, 6, v2
	v_ashrrev_i32_e32 v59, 6, v4
	v_ashrrev_i32_e32 v60, 6, v5
	v_ashrrev_i32_e32 v61, 6, v6
	v_ashrrev_i32_e32 v62, 6, v7
	v_ashrrev_i32_e32 v63, 6, v8
	v_ashrrev_i32_e32 v64, 6, v0
	s_addc_u32 s3, s89, 0
	v_add_u32_e32 v1, 0, v1
	v_mul_lo_u32 v9, v57, s23
	v_mul_lo_u32 v10, v58, s23
	v_mul_lo_u32 v11, v59, s23
	v_mul_lo_u32 v12, v60, s23
	v_mul_lo_u32 v13, v61, s23
	v_mul_lo_u32 v14, v62, s23
	v_mul_lo_u32 v15, v63, s23
	v_mul_lo_u32 v16, v64, s23
	v_ashrrev_i32_e32 v65, 4, v2
	v_ashrrev_i32_e32 v67, 4, v4
	v_ashrrev_i32_e32 v69, 4, v5
	v_ashrrev_i32_e32 v71, 4, v6
	v_ashrrev_i32_e32 v73, 4, v7
	v_ashrrev_i32_e32 v75, 4, v8
	v_ashrrev_i32_e32 v77, 4, v0
	v_lshl_add_u64 v[34:35], s[2:3], 0, v[32:33]
	v_lshl_add_u32 v56, v53, 2, v3
	v_lshl_add_u32 v66, v65, 2, v3
	v_lshl_add_u32 v68, v67, 2, v3
	v_lshl_add_u32 v70, v69, 2, v3
	v_lshl_add_u32 v72, v71, 2, v3
	v_lshl_add_u32 v74, v73, 2, v3
	v_lshl_add_u32 v76, v75, 2, v3
	v_lshl_add_u32 v78, v77, 2, v3
	s_lshl_b32 s4, s30, 6
	s_lshl_b32 s31, s94, 6
	v_add_u32_e32 v79, v1, v10
	v_add_u32_e32 v80, v1, v12
	v_add_u32_e32 v81, v1, v14
	v_add_u32_e32 v82, v1, v16
	v_add_u32_e32 v83, v1, v9
	v_add_u32_e32 v84, v1, v11
	v_add_u32_e32 v85, v1, v13
	v_add_u32_e32 v86, v1, v15
	s_branch .LBB0_43

; #define LAS __attribute__((address_space(3)))
; __device__ __forceinline__ int opq_tid() { int t = threadIdx.x; asm volatile("" : "+v"(t)); return t; }
; __device__ __forceinline__ int opq_bid() { int b = blockIdx.x; asm volatile("" : "+s"(b)); return b; }
; __device__ __forceinline__ f32x4 ld_nt(const float* p) { return __builtin_nontemporal_load((const f32x4*)p); }
; __device__ __forceinline__ void convert_weight_v4(LAS unsigned char* lds, const float* W, bf16_t* Bt, int K, int Nsrc, int Ndst, const float* gain, int mode) {
;     LAS float* tile = (LAS float*)lds;
;     const int tid = opq_tid(), nkt = K / 64, nnt = Ndst / 256;
;     for (int t = opq_bid(); t < nkt * nnt; t += gridDim.x) {
;         const int k0 = (t % nkt) * 64, pn = t / nkt, n0 = pn * 256;
;         f32x4 v[8];
; #pragma unroll
;         for (int i = 0; i < 8; ++i) {
;             const int e = tid + i * 512, kk = e >> 6, n4 = e & 63;
;             const int n = (mode == 1) ? (n4 >> 5) * FF + pn * 128 + (n4 & 31) * 4 : n0 + n4 * 4;
;             v[i] = (f32x4){0.f, 0.f, 0.f, 0.f};
;             if (n < Nsrc) v[i] = ld_nt(W + (size_t)(k0 + kk) * Nsrc + n);
; __device__ __forceinline__ void prologue(LAS unsigned char* lds, const Params& P) {
;     ...
;         convert_weight_v4(lds, in[11] + (size_t)l * FF * D, (bf16_t*)(ws + W_DN + (size_t)(l * 2 + 0) * W_DN_SZ), FF, D, D, nullptr, 0);
.LBB0_58:
	v_mov_b32_e32 v0, v254
	s_movk_i32 s14, 0x7fff
	s_cmpk_gt_i32 s14, 0xaf
	s_mul_i32 s4, s28, 0x2c0000
	s_cbranch_scc1 .LBB0_77
	s_lshl_b64 s[2:3], s[4:5], 2
	s_add_u32 s2, s62, s2
	s_addc_u32 s3, s63, s3
	s_mul_i32 s29, s29, 0x580000
	v_lshlrev_b32_e32 v1, 2, v0
	s_add_u32 s12, s17, s29
	v_and_b32_e32 v38, 0xfc, v1
	v_and_b32_e32 v1, 60, v1
	s_addc_u32 s13, s19, 0
	v_lshlrev_b32_e32 v32, 1, v1
	v_mad_u32_u24 v3, v1, s23, 0
	v_lshl_add_u64 v[34:35], s[12:13], 0, v[32:33]
	v_ashrrev_i32_e32 v32, 4, v0
	v_ashrrev_i32_e32 v40, 6, v0
	v_add_u32_e32 v1, 0x200, v0
	v_add_u32_e32 v4, 0x400, v0
	v_add_u32_e32 v5, 0x600, v0
	v_add_u32_e32 v6, 0x800, v0
	v_add_u32_e32 v7, 0xa00, v0
	v_add_u32_e32 v8, 0xc00, v0
	v_add_u32_e32 v0, 0xe00, v0
	v_ashrrev_i32_e32 v41, 6, v1
	v_ashrrev_i32_e32 v42, 6, v4
	v_ashrrev_i32_e32 v43, 6, v5
	v_ashrrev_i32_e32 v44, 6, v6
	v_ashrrev_i32_e32 v45, 6, v7
	v_ashrrev_i32_e32 v46, 6, v8
	v_ashrrev_i32_e32 v47, 6, v0
	v_lshl_add_u32 v2, v38, 2, 0
	v_mul_lo_u32 v9, v40, s23
	v_mul_lo_u32 v10, v41, s23
	v_mul_lo_u32 v11, v42, s23
	v_mul_lo_u32 v12, v43, s23
	v_mul_lo_u32 v13, v44, s23
	v_mul_lo_u32 v14, v45, s23
	v_mul_lo_u32 v15, v46, s23
	v_mul_lo_u32 v16, v47, s23
	v_ashrrev_i32_e32 v48, 4, v1
	v_ashrrev_i32_e32 v50, 4, v4
	v_ashrrev_i32_e32 v52, 4, v5
	v_ashrrev_i32_e32 v56, 4, v6
	v_ashrrev_i32_e32 v58, 4, v7
	v_ashrrev_i32_e32 v60, 4, v8
	v_ashrrev_i32_e32 v62, 4, v0
	v_lshl_add_u32 v39, v32, 2, v3
	v_lshl_add_u32 v49, v48, 2, v3
	v_lshl_add_u32 v51, v50, 2, v3
	v_lshl_add_u32 v53, v52, 2, v3
	v_lshl_add_u32 v57, v56, 2, v3
	v_lshl_add_u32 v59, v58, 2, v3
	v_lshl_add_u32 v61, v60, 2, v3
	v_lshl_add_u32 v63, v62, 2, v3
	s_lshl_b32 s15, s14, 6
	s_lshl_b32 s20, s94, 6
	v_add_u32_e32 v64, v2, v9
	v_add_u32_e32 v65, v2, v10
	v_add_u32_e32 v66, v2, v11
	v_add_u32_e32 v67, v2, v12
	v_add_u32_e32 v68, v2, v13
	v_add_u32_e32 v69, v2, v14
	v_add_u32_e32 v70, v2, v15
	v_add_u32_e32 v71, v2, v16
	s_branch .LBB0_61

; #define LAS __attribute__((address_space(3)))
; __device__ __forceinline__ int opq_tid() { int t = threadIdx.x; asm volatile("" : "+v"(t)); return t; }
; __device__ __forceinline__ int opq_bid() { int b = blockIdx.x; asm volatile("" : "+s"(b)); return b; }
; __device__ __forceinline__ f32x4 ld_nt(const float* p) { return __builtin_nontemporal_load((const f32x4*)p); }
; __device__ __forceinline__ void convert_weight_v4(LAS unsigned char* lds, const float* W, bf16_t* Bt, int K, int Nsrc, int Ndst, const float* gain, int mode) {
;     LAS float* tile = (LAS float*)lds;
;     const int tid = opq_tid(), nkt = K / 64, nnt = Ndst / 256;
;     for (int t = opq_bid(); t < nkt * nnt; t += gridDim.x) {
;         const int k0 = (t % nkt) * 64, pn = t / nkt, n0 = pn * 256;
;         f32x4 v[8];
; #pragma unroll
;         for (int i = 0; i < 8; ++i) {
;             const int e = tid + i * 512, kk = e >> 6, n4 = e & 63;
;             const int n = (mode == 1) ? (n4 >> 5) * FF + pn * 128 + (n4 & 31) * 4 : n0 + n4 * 4;
;             v[i] = (f32x4){0.f, 0.f, 0.f, 0.f};
;             if (n < Nsrc) v[i] = ld_nt(W + (size_t)(k0 + kk) * Nsrc + n);
; __device__ __forceinline__ void prologue(LAS unsigned char* lds, const Params& P) {
;     ...
;         convert_weight_v4(lds, in[15] + (size_t)l * FF * D, (bf16_t*)(ws + W_DN + (size_t)(l * 2 + 1) * W_DN_SZ), FF, D, D, nullptr, 0);
.LBB0_77:
	v_mov_b32_e32 v0, v254
	s_movk_i32 s14, 0x7fff
	s_cmpk_gt_i32 s14, 0xaf
	s_cbranch_scc1 .LBB0_19
	s_lshl_b64 s[2:3], s[4:5], 2
	s_add_u32 s2, s70, s2
	s_addc_u32 s3, s71, s3
	s_mul_i32 s27, s27, 0x580000
	v_lshlrev_b32_e32 v1, 2, v0
	s_add_u32 s12, s17, s27
	v_and_b32_e32 v38, 0xfc, v1
	v_and_b32_e32 v1, 60, v1
	s_addc_u32 s13, s19, 0
	v_lshlrev_b32_e32 v32, 1, v1
	v_mad_u32_u24 v3, v1, s23, 0
	v_lshl_add_u64 v[34:35], s[12:13], 0, v[32:33]
	v_ashrrev_i32_e32 v32, 4, v0
	v_ashrrev_i32_e32 v40, 6, v0
	v_add_u32_e32 v1, 0x200, v0
	v_add_u32_e32 v4, 0x400, v0
	v_add_u32_e32 v5, 0x600, v0
	v_add_u32_e32 v6, 0x800, v0
	v_add_u32_e32 v7, 0xa00, v0
	v_add_u32_e32 v8, 0xc00, v0
	v_add_u32_e32 v0, 0xe00, v0
	v_ashrrev_i32_e32 v41, 6, v1
	v_ashrrev_i32_e32 v42, 6, v4
	v_ashrrev_i32_e32 v43, 6, v5
	v_ashrrev_i32_e32 v44, 6, v6
	v_ashrrev_i32_e32 v45, 6, v7
	v_ashrrev_i32_e32 v46, 6, v8
	v_ashrrev_i32_e32 v47, 6, v0
	v_lshl_add_u32 v2, v38, 2, 0
	v_mul_lo_u32 v9, v40, s23
	v_mul_lo_u32 v10, v41, s23
	v_mul_lo_u32 v11, v42, s23
	v_mul_lo_u32 v12, v43, s23
	v_mul_lo_u32 v13, v44, s23
	v_mul_lo_u32 v14, v45, s23
	v_mul_lo_u32 v15, v46, s23
	v_mul_lo_u32 v16, v47, s23
	v_ashrrev_i32_e32 v48, 4, v1
	v_ashrrev_i32_e32 v50, 4, v4
	v_ashrrev_i32_e32 v52, 4, v5
	v_ashrrev_i32_e32 v56, 4, v6
	v_ashrrev_i32_e32 v58, 4, v7
	v_ashrrev_i32_e32 v60, 4, v8
	v_ashrrev_i32_e32 v62, 4, v0
	v_lshl_add_u32 v39, v32, 2, v3
	v_lshl_add_u32 v49, v48, 2, v3
	v_lshl_add_u32 v51, v50, 2, v3
	v_lshl_add_u32 v53, v52, 2, v3
	v_lshl_add_u32 v57, v56, 2, v3
	v_lshl_add_u32 v59, v58, 2, v3
	v_lshl_add_u32 v61, v60, 2, v3
	v_lshl_add_u32 v63, v62, 2, v3
	s_lshl_b32 s4, s14, 6
	s_lshl_b32 s15, s94, 6
	v_add_u32_e32 v64, v2, v9
	v_add_u32_e32 v65, v2, v10
	v_add_u32_e32 v66, v2, v11
	v_add_u32_e32 v67, v2, v12
	v_add_u32_e32 v68, v2, v13
	v_add_u32_e32 v69, v2, v14
	v_add_u32_e32 v70, v2, v15
	v_add_u32_e32 v71, v2, v16
	s_branch .LBB0_80

; #define LAS __attribute__((address_space(3)))
; __device__ __forceinline__ int opq_tid() { int t = threadIdx.x; asm volatile("" : "+v"(t)); return t; }
; __device__ __forceinline__ int opq_bid() { int b = blockIdx.x; asm volatile("" : "+s"(b)); return b; }
; __device__ __forceinline__ f32x4 ld_nt(const float* p) { return __builtin_nontemporal_load((const f32x4*)p); }
; __device__ __forceinline__ void convert_weight_v4(LAS unsigned char* lds, const float* W, bf16_t* Bt, int K, int Nsrc, int Ndst, const float* gain, int mode) {
;     LAS float* tile = (LAS float*)lds;
;     const int tid = opq_tid(), nkt = K / 64, nnt = Ndst / 256;
;     for (int t = opq_bid(); t < nkt * nnt; t += gridDim.x) {
;         const int k0 = (t % nkt) * 64, pn = t / nkt, n0 = pn * 256;
;         f32x4 v[8];
; #pragma unroll
;         for (int i = 0; i < 8; ++i) {
;             const int e = tid + i * 512, kk = e >> 6, n4 = e & 63;
;             const int n = (mode == 1) ? (n4 >> 5) * FF + pn * 128 + (n4 & 31) * 4 : n0 + n4 * 4;
;             v[i] = (f32x4){0.f, 0.f, 0.f, 0.f};
;             if (n < Nsrc) v[i] = ld_nt(W + (size_t)(k0 + kk) * Nsrc + n);
; __device__ __forceinline__ void prologue(LAS unsigned char* lds, const Params& P) {
;     ...
;     convert_weight_v4(lds, in[16], (bf16_t*)(ws + W_IN0), D, 3072, 3072, in[12], 0);
.LBB0_96:
	v_mov_b32_e32 v0, v254
	s_movk_i32 s8, 0x7fff
	s_cmpk_gt_i32 s8, 0xbf
	s_cbranch_scc1 .LBB0_131
	v_lshlrev_b32_e32 v1, 2, v0
	v_and_b32_e32 v36, 0xfc, v1
	v_and_b32_e32 v1, 60, v1
	v_lshlrev_b32_e32 v2, 1, v1
	v_mov_b32_e32 v3, 0
	s_movk_i32 s6, 0x404
	v_lshl_add_u64 v[2:3], s[88:89], 0, v[2:3]
	s_mov_b64 s[2:3], 0x4200000
	v_mad_u32_u24 v5, v1, s6, 0
	v_lshl_add_u64 v[32:33], v[2:3], 0, s[2:3]
	v_ashrrev_i32_e32 v37, 4, v0
	v_ashrrev_i32_e32 v39, 6, v0
	v_add_u32_e32 v1, 0x200, v0
	v_add_u32_e32 v2, 0x400, v0
	v_add_u32_e32 v3, 0x600, v0
	v_add_u32_e32 v6, 0x800, v0
	v_add_u32_e32 v7, 0xa00, v0
	v_add_u32_e32 v8, 0xc00, v0
	v_add_u32_e32 v0, 0xe00, v0
	v_ashrrev_i32_e32 v40, 6, v1
	v_ashrrev_i32_e32 v41, 6, v2
	v_ashrrev_i32_e32 v42, 6, v3
	v_ashrrev_i32_e32 v43, 6, v6
	v_ashrrev_i32_e32 v44, 6, v7
	v_ashrrev_i32_e32 v45, 6, v8
	v_ashrrev_i32_e32 v46, 6, v0
	s_cmp_lg_u64 s[64:65], 0
	v_lshl_add_u32 v4, v36, 2, 0
	v_mul_lo_u32 v9, v39, s6
	v_mul_lo_u32 v10, v40, s6
	v_mul_lo_u32 v11, v41, s6
	v_mul_lo_u32 v12, v42, s6
	v_mul_lo_u32 v13, v43, s6
	v_mul_lo_u32 v14, v44, s6
	v_mul_lo_u32 v15, v45, s6
	v_mul_lo_u32 v16, v46, s6
	v_ashrrev_i32_e32 v47, 4, v1
	v_ashrrev_i32_e32 v49, 4, v2
	v_ashrrev_i32_e32 v51, 4, v3
	v_ashrrev_i32_e32 v53, 4, v6
	v_ashrrev_i32_e32 v56, 4, v7
	v_ashrrev_i32_e32 v58, 4, v8
	v_ashrrev_i32_e32 v60, 4, v0
	s_cselect_b64 s[4:5], -1, 0
	v_lshl_add_u32 v38, v37, 2, v5
	s_movk_i32 s9, 0xc00
	v_lshl_add_u32 v48, v47, 2, v5
	v_lshl_add_u32 v50, v49, 2, v5
	v_lshl_add_u32 v52, v51, 2, v5
	v_lshl_add_u32 v55, v53, 2, v5
	v_lshl_add_u32 v57, v56, 2, v5
	v_lshl_add_u32 v59, v58, 2, v5
	v_lshl_add_u32 v61, v60, 2, v5
	s_lshl_b32 s10, s8, 6
	s_lshl_b32 s11, s94, 6
	s_movk_i32 s12, 0x3000
	v_add_u32_e32 v62, v4, v10
	v_add_u32_e32 v63, v4, v12
	v_add_u32_e32 v64, v4, v14
	v_add_u32_e32 v65, v4, v16
	v_add_u32_e32 v66, v4, v9
	v_add_u32_e32 v67, v4, v11
	v_add_u32_e32 v68, v4, v13
	v_add_u32_e32 v69, v4, v15
	s_branch .LBB0_100

; #define LAS __attribute__((address_space(3)))
; __device__ __forceinline__ int opq_tid() { int t = threadIdx.x; asm volatile("" : "+v"(t)); return t; }
; __device__ __forceinline__ int opq_bid() { int b = blockIdx.x; asm volatile("" : "+s"(b)); return b; }
; __device__ __forceinline__ f32x4 ld_nt(const float* p) { return __builtin_nontemporal_load((const f32x4*)p); }
; __device__ __forceinline__ void convert_weight_v4(LAS unsigned char* lds, const float* W, bf16_t* Bt, int K, int Nsrc, int Ndst, const float* gain, int mode) {
;     LAS float* tile = (LAS float*)lds;
;     const int tid = opq_tid(), nkt = K / 64, nnt = Ndst / 256;
;     for (int t = opq_bid(); t < nkt * nnt; t += gridDim.x) {
;         const int k0 = (t % nkt) * 64, pn = t / nkt, n0 = pn * 256;
;         f32x4 v[8];
; #pragma unroll
;         for (int i = 0; i < 8; ++i) {
;             const int e = tid + i * 512, kk = e >> 6, n4 = e & 63;
;             const int n = (mode == 1) ? (n4 >> 5) * FF + pn * 128 + (n4 & 31) * 4 : n0 + n4 * 4;
;             v[i] = (f32x4){0.f, 0.f, 0.f, 0.f};
;             if (n < Nsrc) v[i] = ld_nt(W + (size_t)(k0 + kk) * Nsrc + n);
; __device__ __forceinline__ void prologue(LAS unsigned char* lds, const Params& P) {
;     ...
;     convert_weight_v4(lds, in[23], (bf16_t*)(ws + W_OUT0), D, D, D, nullptr, 0);
.LBB0_131:
	v_mov_b32_e32 v0, v254
	s_movk_i32 s4, 0x7fff
	s_cmp_gt_i32 s4, 63
	s_cbranch_scc1 .LBB0_150
	v_lshlrev_b32_e32 v1, 2, v0
	v_and_b32_e32 v36, 0xfc, v1
	v_and_b32_e32 v1, 60, v1
	v_lshlrev_b32_e32 v2, 1, v1
	v_mov_b32_e32 v3, 0
	s_movk_i32 s6, 0x404
	v_lshl_add_u64 v[2:3], s[88:89], 0, v[2:3]
	s_mov_b64 s[2:3], 0x4800000
	v_mad_u32_u24 v5, v1, s6, 0
	v_lshl_add_u64 v[32:33], v[2:3], 0, s[2:3]
	v_ashrrev_i32_e32 v37, 4, v0
	v_ashrrev_i32_e32 v39, 6, v0
	v_add_u32_e32 v1, 0x200, v0
	v_add_u32_e32 v2, 0x400, v0
	v_add_u32_e32 v3, 0x600, v0
	v_add_u32_e32 v6, 0x800, v0
	v_add_u32_e32 v7, 0xa00, v0
	v_add_u32_e32 v8, 0xc00, v0
	v_add_u32_e32 v0, 0xe00, v0
	v_ashrrev_i32_e32 v40, 6, v1
	v_ashrrev_i32_e32 v41, 6, v2
	v_ashrrev_i32_e32 v42, 6, v3
	v_ashrrev_i32_e32 v43, 6, v6
	v_ashrrev_i32_e32 v44, 6, v7
	v_ashrrev_i32_e32 v45, 6, v8
	v_ashrrev_i32_e32 v46, 6, v0
	v_lshl_add_u32 v4, v36, 2, 0
	v_mul_lo_u32 v9, v39, s6
	v_mul_lo_u32 v10, v40, s6
	v_mul_lo_u32 v11, v41, s6
	v_mul_lo_u32 v12, v42, s6
	v_mul_lo_u32 v13, v43, s6
	v_mul_lo_u32 v14, v44, s6
	v_mul_lo_u32 v15, v45, s6
	v_mul_lo_u32 v16, v46, s6
	v_ashrrev_i32_e32 v47, 4, v1
	v_ashrrev_i32_e32 v49, 4, v2
	v_ashrrev_i32_e32 v51, 4, v3
	v_ashrrev_i32_e32 v53, 4, v6
	v_ashrrev_i32_e32 v56, 4, v7
	v_ashrrev_i32_e32 v58, 4, v8
	v_ashrrev_i32_e32 v60, 4, v0
	v_lshl_add_u32 v38, v37, 2, v5
	s_movk_i32 s5, 0x400
	v_lshl_add_u32 v48, v47, 2, v5
	v_lshl_add_u32 v50, v49, 2, v5
	v_lshl_add_u32 v52, v51, 2, v5
	v_lshl_add_u32 v55, v53, 2, v5
	v_lshl_add_u32 v57, v56, 2, v5
	v_lshl_add_u32 v59, v58, 2, v5
	v_lshl_add_u32 v61, v60, 2, v5
	s_lshl_b32 s6, s4, 6
	s_lshl_b32 s7, s94, 6
	v_add_u32_e32 v62, v4, v9
	v_add_u32_e32 v63, v4, v10
	v_add_u32_e32 v64, v4, v11
	v_add_u32_e32 v65, v4, v12
	v_add_u32_e32 v66, v4, v13
	v_add_u32_e32 v67, v4, v14
	v_add_u32_e32 v68, v4, v15
	v_add_u32_e32 v69, v4, v16
	s_branch .LBB0_134

; #define LAS __attribute__((address_space(3)))
; __device__ __forceinline__ int opq_tid() { int t = threadIdx.x; asm volatile("" : "+v"(t)); return t; }
; __device__ __forceinline__ int opq_bid() { int b = blockIdx.x; asm volatile("" : "+s"(b)); return b; }
; __device__ __forceinline__ f32x4 ld_nt(const float* p) { return __builtin_nontemporal_load((const f32x4*)p); }
; __device__ __forceinline__ void convert_weight_v4(LAS unsigned char* lds, const float* W, bf16_t* Bt, int K, int Nsrc, int Ndst, const float* gain, int mode) {
;     LAS float* tile = (LAS float*)lds;
;     const int tid = opq_tid(), nkt = K / 64, nnt = Ndst / 256;
;     for (int t = opq_bid(); t < nkt * nnt; t += gridDim.x) {
;         const int k0 = (t % nkt) * 64, pn = t / nkt, n0 = pn * 256;
;         f32x4 v[8];
; #pragma unroll
;         for (int i = 0; i < 8; ++i) {
;             const int e = tid + i * 512, kk = e >> 6, n4 = e & 63;
;             const int n = (mode == 1) ? (n4 >> 5) * FF + pn * 128 + (n4 & 31) * 4 : n0 + n4 * 4;
;             v[i] = (f32x4){0.f, 0.f, 0.f, 0.f};
;             if (n < Nsrc) v[i] = ld_nt(W + (size_t)(k0 + kk) * Nsrc + n);
; __device__ __forceinline__ void prologue(LAS unsigned char* lds, const Params& P) {
;     ...
;     convert_weight_v4(lds, in[24], (bf16_t*)(ws + W_IN1), D, 672, 768, in[12] + D, 0);
.LBB0_150:
	v_mov_b32_e32 v0, v254
	s_movk_i32 s8, 0x7fff
	s_cmp_gt_i32 s8, 47
	s_cbranch_scc1 .LBB0_169
	v_lshlrev_b32_e32 v1, 2, v0
	v_and_b32_e32 v38, 0xfc, v1
	v_and_b32_e32 v1, 60, v1
	v_lshlrev_b32_e32 v2, 1, v1
	v_mov_b32_e32 v3, 0
	s_movk_i32 s6, 0x404
	v_lshl_add_u64 v[2:3], s[88:89], 0, v[2:3]
	s_mov_b64 s[4:5], 0x4a00000
	v_mad_u32_u24 v5, v1, s6, 0
	v_lshl_add_u64 v[32:33], v[2:3], 0, s[4:5]
	v_ashrrev_i32_e32 v39, 4, v0
	v_ashrrev_i32_e32 v41, 6, v0
	v_add_u32_e32 v1, 0x200, v0
	v_add_u32_e32 v2, 0x400, v0
	v_add_u32_e32 v3, 0x600, v0
	v_add_u32_e32 v6, 0x800, v0
	v_add_u32_e32 v7, 0xa00, v0
	v_add_u32_e32 v8, 0xc00, v0
	v_add_u32_e32 v0, 0xe00, v0
	v_ashrrev_i32_e32 v42, 6, v1
	v_ashrrev_i32_e32 v43, 6, v2
	v_ashrrev_i32_e32 v44, 6, v3
	v_ashrrev_i32_e32 v45, 6, v6
	v_ashrrev_i32_e32 v46, 6, v7
	v_ashrrev_i32_e32 v47, 6, v8
	v_ashrrev_i32_e32 v48, 6, v0
	s_add_u32 s2, s64, 0x1000
	v_lshl_add_u32 v4, v38, 2, 0
	v_mul_lo_u32 v9, v41, s6
	v_mul_lo_u32 v10, v42, s6
	v_mul_lo_u32 v11, v43, s6
	v_mul_lo_u32 v12, v44, s6
	v_mul_lo_u32 v13, v45, s6
	v_mul_lo_u32 v14, v46, s6
	v_mul_lo_u32 v15, v47, s6
	v_mul_lo_u32 v16, v48, s6
	v_ashrrev_i32_e32 v49, 4, v1
	v_ashrrev_i32_e32 v51, 4, v2
	v_ashrrev_i32_e32 v53, 4, v3
	v_ashrrev_i32_e32 v56, 4, v6
	v_ashrrev_i32_e32 v58, 4, v7
	v_ashrrev_i32_e32 v60, 4, v8
	v_ashrrev_i32_e32 v62, 4, v0
	s_addc_u32 s3, s65, 0
	v_lshl_add_u32 v40, v39, 2, v5
	v_lshl_add_u32 v50, v49, 2, v5
	v_lshl_add_u32 v52, v51, 2, v5
	v_lshl_add_u32 v55, v53, 2, v5
	v_lshl_add_u32 v57, v56, 2, v5
	v_lshl_add_u32 v59, v58, 2, v5
	v_lshl_add_u32 v61, v60, 2, v5
	v_lshl_add_u32 v63, v62, 2, v5
	s_lshl_b32 s9, s8, 6
	s_lshl_b32 s10, s94, 6
	s_movk_i32 s11, 0x2a0
	s_movk_i32 s12, 0xa80
	v_add_u32_e32 v64, v4, v9
	v_add_u32_e32 v65, v4, v10
	v_add_u32_e32 v66, v4, v11
	v_add_u32_e32 v67, v4, v12
	v_add_u32_e32 v68, v4, v13
	v_add_u32_e32 v69, v4, v14
	v_add_u32_e32 v70, v4, v15
	v_add_u32_e32 v71, v4, v16
	s_branch .LBB0_153

; #define LAS __attribute__((address_space(3)))
; __device__ __forceinline__ int opq_tid() { int t = threadIdx.x; asm volatile("" : "+v"(t)); return t; }
; __device__ __forceinline__ int opq_bid() { int b = blockIdx.x; asm volatile("" : "+s"(b)); return b; }
; __device__ __forceinline__ f32x4 ld_nt(const float* p) { return __builtin_nontemporal_load((const f32x4*)p); }
; __device__ __forceinline__ void convert_weight_v4(LAS unsigned char* lds, const float* W, bf16_t* Bt, int K, int Nsrc, int Ndst, const float* gain, int mode) {
;     LAS float* tile = (LAS float*)lds;
;     const int tid = opq_tid(), nkt = K / 64, nnt = Ndst / 256;
;     for (int t = opq_bid(); t < nkt * nnt; t += gridDim.x) {
;         const int k0 = (t % nkt) * 64, pn = t / nkt, n0 = pn * 256;
;         f32x4 v[8];
; #pragma unroll
;         for (int i = 0; i < 8; ++i) {
;             const int e = tid + i * 512, kk = e >> 6, n4 = e & 63;
;             const int n = (mode == 1) ? (n4 >> 5) * FF + pn * 128 + (n4 & 31) * 4 : n0 + n4 * 4;
;             v[i] = (f32x4){0.f, 0.f, 0.f, 0.f};
;             if (n < Nsrc) v[i] = ld_nt(W + (size_t)(k0 + kk) * Nsrc + n);
; __device__ __forceinline__ void prologue(LAS unsigned char* lds, const Params& P) {
;     ...
;     convert_weight_v4(lds, in[28], (bf16_t*)(ws + W_KVUP), 256, 2048, 2048, nullptr, 0);
.LBB0_188:
	v_mov_b32_e32 v0, v254
	s_movk_i32 s4, 0x7fff
	s_cmp_gt_i32 s4, 31
	s_cbranch_scc1 .LBB0_207
	v_lshlrev_b32_e32 v1, 2, v0
	v_and_b32_e32 v36, 0xfc, v1
	v_and_b32_e32 v1, 60, v1
	v_lshlrev_b32_e32 v2, 1, v1
	v_mov_b32_e32 v3, 0
	s_movk_i32 s6, 0x404
	v_lshl_add_u64 v[2:3], s[88:89], 0, v[2:3]
	s_mov_b64 s[2:3], 0x4ca0000
	v_mad_u32_u24 v5, v1, s6, 0
	v_lshl_add_u64 v[32:33], v[2:3], 0, s[2:3]
	v_ashrrev_i32_e32 v37, 4, v0
	v_ashrrev_i32_e32 v39, 6, v0
	v_add_u32_e32 v1, 0x200, v0
	v_add_u32_e32 v2, 0x400, v0
	v_add_u32_e32 v3, 0x600, v0
	v_add_u32_e32 v6, 0x800, v0
	v_add_u32_e32 v7, 0xa00, v0
	v_add_u32_e32 v8, 0xc00, v0
	v_add_u32_e32 v0, 0xe00, v0
	v_ashrrev_i32_e32 v40, 6, v1
	v_ashrrev_i32_e32 v41, 6, v2
	v_ashrrev_i32_e32 v42, 6, v3
	v_ashrrev_i32_e32 v43, 6, v6
	v_ashrrev_i32_e32 v44, 6, v7
	v_ashrrev_i32_e32 v45, 6, v8
	v_ashrrev_i32_e32 v46, 6, v0
	v_lshl_add_u32 v4, v36, 2, 0
	v_mul_lo_u32 v9, v39, s6
	v_mul_lo_u32 v10, v40, s6
	v_mul_lo_u32 v11, v41, s6
	v_mul_lo_u32 v12, v42, s6
	v_mul_lo_u32 v13, v43, s6
	v_mul_lo_u32 v14, v44, s6
	v_mul_lo_u32 v15, v45, s6
	v_mul_lo_u32 v16, v46, s6
	v_ashrrev_i32_e32 v47, 4, v1
	v_ashrrev_i32_e32 v49, 4, v2
	v_ashrrev_i32_e32 v51, 4, v3
	v_ashrrev_i32_e32 v53, 4, v6
	v_ashrrev_i32_e32 v56, 4, v7
	v_ashrrev_i32_e32 v58, 4, v8
	v_ashrrev_i32_e32 v60, 4, v0
	v_lshl_add_u32 v38, v37, 2, v5
	s_movk_i32 s5, 0x800
	v_lshl_add_u32 v48, v47, 2, v5
	v_lshl_add_u32 v50, v49, 2, v5
	v_lshl_add_u32 v52, v51, 2, v5
	v_lshl_add_u32 v55, v53, 2, v5
	v_lshl_add_u32 v57, v56, 2, v5
	v_lshl_add_u32 v59, v58, 2, v5
	v_lshl_add_u32 v61, v60, 2, v5
	s_lshl_b32 s6, s4, 6
	s_lshl_b32 s7, s94, 6
	v_add_u32_e32 v62, v4, v9
	v_add_u32_e32 v63, v4, v10
	v_add_u32_e32 v64, v4, v11
	v_add_u32_e32 v65, v4, v12
	v_add_u32_e32 v66, v4, v13
	v_add_u32_e32 v67, v4, v14
	v_add_u32_e32 v68, v4, v15
	v_add_u32_e32 v69, v4, v16
	s_branch .LBB0_191

; #define LAS __attribute__((address_space(3)))
; __device__ __forceinline__ int opq_tid() { int t = threadIdx.x; asm volatile("" : "+v"(t)); return t; }
; __device__ __forceinline__ int opq_bid() { int b = blockIdx.x; asm volatile("" : "+s"(b)); return b; }
; __device__ __forceinline__ f32x4 ld_nt(const float* p) { return __builtin_nontemporal_load((const f32x4*)p); }
; __device__ __forceinline__ void convert_weight_v4(LAS unsigned char* lds, const float* W, bf16_t* Bt, int K, int Nsrc, int Ndst, const float* gain, int mode) {
;     LAS float* tile = (LAS float*)lds;
;     const int tid = opq_tid(), nkt = K / 64, nnt = Ndst / 256;
;     for (int t = opq_bid(); t < nkt * nnt; t += gridDim.x) {
;         const int k0 = (t % nkt) * 64, pn = t / nkt, n0 = pn * 256;
;         f32x4 v[8];
; #pragma unroll
;         for (int i = 0; i < 8; ++i) {
;             const int e = tid + i * 512, kk = e >> 6, n4 = e & 63;
;             const int n = (mode == 1) ? (n4 >> 5) * FF + pn * 128 + (n4 & 31) * 4 : n0 + n4 * 4;
;             v[i] = (f32x4){0.f, 0.f, 0.f, 0.f};
;             if (n < Nsrc) v[i] = ld_nt(W + (size_t)(k0 + kk) * Nsrc + n);
; __device__ __forceinline__ void prologue(LAS unsigned char* lds, const Params& P) {
;     ...
;     convert_weight_v4(lds, in[29], (bf16_t*)(ws + W_OUT1), D, D, D, nullptr, 0);
.LBB0_207:
	v_mov_b32_e32 v0, v254
	s_movk_i32 s4, 0x7fff
	s_cmp_gt_i32 s4, 63
	s_cbranch_scc1 .LBB0_226
	v_lshlrev_b32_e32 v1, 2, v0
	v_and_b32_e32 v36, 0xfc, v1
	v_and_b32_e32 v1, 60, v1
	v_lshlrev_b32_e32 v2, 1, v1
	v_mov_b32_e32 v3, 0
	s_movk_i32 s6, 0x404
	v_lshl_add_u64 v[2:3], s[88:89], 0, v[2:3]
	s_mov_b64 s[2:3], 0x4da0000
	v_mad_u32_u24 v5, v1, s6, 0
	v_lshl_add_u64 v[32:33], v[2:3], 0, s[2:3]
	v_ashrrev_i32_e32 v37, 4, v0
	v_ashrrev_i32_e32 v39, 6, v0
	v_add_u32_e32 v1, 0x200, v0
	v_add_u32_e32 v2, 0x400, v0
	v_add_u32_e32 v3, 0x600, v0
	v_add_u32_e32 v6, 0x800, v0
	v_add_u32_e32 v7, 0xa00, v0
	v_add_u32_e32 v8, 0xc00, v0
	v_add_u32_e32 v0, 0xe00, v0
	v_ashrrev_i32_e32 v40, 6, v1
	v_ashrrev_i32_e32 v41, 6, v2
	v_ashrrev_i32_e32 v42, 6, v3
	v_ashrrev_i32_e32 v43, 6, v6
	v_ashrrev_i32_e32 v44, 6, v7
	v_ashrrev_i32_e32 v45, 6, v8
	v_ashrrev_i32_e32 v46, 6, v0
	v_lshl_add_u32 v4, v36, 2, 0
	v_mul_lo_u32 v9, v39, s6
	v_mul_lo_u32 v10, v40, s6
	v_mul_lo_u32 v11, v41, s6
	v_mul_lo_u32 v12, v42, s6
	v_mul_lo_u32 v13, v43, s6
	v_mul_lo_u32 v14, v44, s6
	v_mul_lo_u32 v15, v45, s6
	v_mul_lo_u32 v16, v46, s6
	v_ashrrev_i32_e32 v47, 4, v1
	v_ashrrev_i32_e32 v49, 4, v2
	v_ashrrev_i32_e32 v51, 4, v3
	v_ashrrev_i32_e32 v53, 4, v6
	v_ashrrev_i32_e32 v56, 4, v7
	v_ashrrev_i32_e32 v58, 4, v8
	v_ashrrev_i32_e32 v60, 4, v0
	v_lshl_add_u32 v38, v37, 2, v5
	s_movk_i32 s5, 0x400
	v_lshl_add_u32 v48, v47, 2, v5
	v_lshl_add_u32 v50, v49, 2, v5
	v_lshl_add_u32 v52, v51, 2, v5
	v_lshl_add_u32 v55, v53, 2, v5
	v_lshl_add_u32 v57, v56, 2, v5
	v_lshl_add_u32 v59, v58, 2, v5
	v_lshl_add_u32 v61, v60, 2, v5
	s_lshl_b32 s6, s4, 6
	s_lshl_b32 s7, s94, 6
	v_add_u32_e32 v62, v4, v9
	v_add_u32_e32 v63, v4, v10
	v_add_u32_e32 v64, v4, v11
	v_add_u32_e32 v65, v4, v12
	v_add_u32_e32 v66, v4, v13
	v_add_u32_e32 v67, v4, v14
	v_add_u32_e32 v68, v4, v15
	v_add_u32_e32 v69, v4, v16
	s_branch .LBB0_210
